# attention: 16 softmax-denominator LDS reads hoisted ahead of the normalise chain (both local-mode copies); plus K-loop handoff trim and early L1 invalidate in local barrier
# speedup vs baseline: 1.0051x; 1.0051x over previous
; #define PG8_STAGE(bufoff, gbase, voff) do { _Pragma("unroll") for (int _i = 0; _i < 2; ++_i) \
;         __builtin_amdgcn_global_load_lds((const unsigned*)((const char*)(gbase) + (voff)[_i]), (PG8_LAS unsigned*)(lds + (bufoff) + ldsw + _i * 8192), 16, 0, 0); } while (0)
; #define PG8_LDA(dst, b, h) do { _Pragma("unroll") for (int m = 0; m < 4; ++m) _Pragma("unroll") for (int k = 0; k < 2; ++k) dst[m][k] = *(const PG8_LAS bf16x8*)(lds + PG8_SA(b, h) + aoff + m * 2048 + k * 1024); } while (0)
; #define PG8_LDB(dst, b, h) do { _Pragma("unroll") for (int n = 0; n < 2; ++n) _Pragma("unroll") for (int k = 0; k < 2; ++k) dst[n][k] = *(const PG8_LAS bf16x8*)(lds + PG8_SB(b, h) + boff + n * 2048 + k * 1024); } while (0)
; #define PG8_MMA(ai, bj, At, Bt) do { __builtin_amdgcn_s_setprio(1); _Pragma("unroll") for (int m = 0; m < 4; ++m) _Pragma("unroll") for (int n = 0; n < 2; ++n) _Pragma("unroll") for (int k = 0; k < 2; ++k) \
;         acc[ai][bj][m][n] = __builtin_amdgcn_mfma_f32_16x16x32_bf16(Bt[n][k], At[m][k], acc[ai][bj][m][n], 0, 0, 0); __builtin_amdgcn_s_setprio(0); } while (0)
; #define PG8_WAIT_V(n) asm volatile("s_waitcnt vmcnt(" #n ")" ::: "memory")
; #define PG8_WAIT_L(n) asm volatile("s_waitcnt lgkmcnt(" #n ")" ::: "memory")
; #define PG8_BAR __builtin_amdgcn_s_barrier()
; #define PG8_SCHED __builtin_amdgcn_sched_barrier(0)
; template <class Epi, class Sched, bool ALIGN_EPI = false, bool SP2 = false, bool HALFM = false>
; __device__ __forceinline__ void gemm_phase(PG8_LAS unsigned char* lds, const Gemm g, const Sched& S, const Epi& E) {
;     ...
;             PG8_LDB(B0, 0, 0); PG8_LDB(B1, 0, 1); PG8_SCHED; PG8_LDA(At, 0, 0); PG8_STAGE(PG8_SA(1, 1), a1 + hstep, voffA);
;             PG8_WAIT_V(8); PG8_WAIT_L(0); PG8_BAR; PG8_MMA(0, 0, At, B0); PG8_MMA(0, 1, At, B1); PG8_BAR; PG8_SCHED;
;             if constexpr (!HALFM) PG8_LDA(At, 0, 1); PG8_STAGE(PG8_SB(0, 0), b2, voffB); PG8_STAGE(PG8_SB(0, 1), b2 + hstep, voffB); PG8_STAGE(PG8_SA(0, 0), a2, voffA);
;             PG8_WAIT_V(8); PG8_WAIT_L(0); PG8_BAR; if constexpr (!HALFM) { PG8_MMA(1, 0, At, B0); PG8_MMA(1, 1, At, B1); } PG8_BAR; PG8_SCHED;
.LBB0_179:
	s_add_u32 s26, s22, 0xfffc0080
	s_addc_u32 s27, s23, -1
	s_and_b64 s[24:25], s[24:25], exec
	s_cselect_b32 s27, s27, s11
	s_cselect_b32 s26, s26, s58
	s_cselect_b32 s25, s63, s9
	s_cselect_b32 s24, s62, s59
	s_add_i32 s65, 0, 0x10000
	v_add_u32_e32 v140, s65, v143
	s_add_i32 s68, 0, 0x14000
	ds_read_b128 v[148:151], v140
	ds_read_b128 v[160:163], v140 offset:1024
	ds_read_b128 v[164:167], v140 offset:2048
	ds_read_b128 v[168:171], v140 offset:3072
	v_add_u32_e32 v140, s68, v143
	ds_read_b128 v[172:175], v140
	ds_read_b128 v[176:179], v140 offset:1024
	ds_read_b128 v[180:183], v140 offset:2048
	ds_read_b128 v[184:187], v140 offset:3072
	v_lshl_add_u64 v[140:141], s[22:23], 0, v[136:137]
	s_add_i32 m0, s47, 0xc000
	ds_read_b128 v[202:205], v146
	ds_read_b128 v[206:209], v146 offset:1024
	ds_read_b128 v[210:213], v146 offset:2048
	ds_read_b128 v[214:217], v146 offset:3072
	ds_read_b128 v[218:221], v146 offset:4096
	ds_read_b128 v[222:225], v146 offset:5120
	ds_read_b128 v[226:229], v146 offset:6144
	ds_read_b128 v[230:233], v146 offset:7168
	global_load_lds_dwordx4 v[140:141], off
	v_lshl_add_u64 v[140:141], s[22:23], 0, v[138:139]
	s_add_i32 m0, s47, 0xe000
	s_nop 0
	global_load_lds_dwordx4 v[140:141], off
	s_waitcnt vmcnt(8)
	s_waitcnt lgkmcnt(0)
	s_setprio 1
	s_barrier
	v_mfma_f32_16x16x32_bf16 v[126:129], v[148:151], v[202:205], v[126:129]
	v_mfma_f32_16x16x32_bf16 v[122:125], v[164:167], v[202:205], v[122:125]
	v_mfma_f32_16x16x32_bf16 v[110:113], v[148:151], v[210:213], v[110:113]
	v_mfma_f32_16x16x32_bf16 v[106:109], v[164:167], v[210:213], v[106:109]
	v_mfma_f32_16x16x32_bf16 v[94:97], v[148:151], v[218:221], v[94:97]
	v_mfma_f32_16x16x32_bf16 v[90:93], v[164:167], v[218:221], v[90:93]
	v_mfma_f32_16x16x32_bf16 v[76:79], v[148:151], v[226:229], v[76:79]
	v_mfma_f32_16x16x32_bf16 v[72:75], v[164:167], v[226:229], v[72:75]
	v_mfma_f32_16x16x32_bf16 v[126:129], v[160:163], v[206:209], v[126:129]
	v_mfma_f32_16x16x32_bf16 v[122:125], v[168:171], v[206:209], v[122:125]
	v_mfma_f32_16x16x32_bf16 v[110:113], v[160:163], v[214:217], v[110:113]
	v_mfma_f32_16x16x32_bf16 v[106:109], v[168:171], v[214:217], v[106:109]
	v_mfma_f32_16x16x32_bf16 v[94:97], v[160:163], v[222:225], v[94:97]
	v_mfma_f32_16x16x32_bf16 v[90:93], v[168:171], v[222:225], v[90:93]
	v_mfma_f32_16x16x32_bf16 v[76:79], v[160:163], v[230:233], v[76:79]
	v_mfma_f32_16x16x32_bf16 v[72:75], v[168:171], v[230:233], v[72:75]
	v_mfma_f32_16x16x32_bf16 v[118:121], v[172:175], v[202:205], v[118:121]
	v_mfma_f32_16x16x32_bf16 v[114:117], v[180:183], v[202:205], v[114:117]
	v_mfma_f32_16x16x32_bf16 v[102:105], v[172:175], v[210:213], v[102:105]
	v_mfma_f32_16x16x32_bf16 v[98:101], v[180:183], v[210:213], v[98:101]
	v_mfma_f32_16x16x32_bf16 v[86:89], v[172:175], v[218:221], v[86:89]
	v_mfma_f32_16x16x32_bf16 v[82:85], v[180:183], v[218:221], v[82:85]
	v_mfma_f32_16x16x32_bf16 v[68:71], v[172:175], v[226:229], v[68:71]
	v_mfma_f32_16x16x32_bf16 v[64:67], v[180:183], v[226:229], v[64:67]
	v_mfma_f32_16x16x32_bf16 v[118:121], v[176:179], v[206:209], v[118:121]
	v_mfma_f32_16x16x32_bf16 v[114:117], v[184:187], v[206:209], v[114:117]
	v_mfma_f32_16x16x32_bf16 v[102:105], v[176:179], v[214:217], v[102:105]
	v_mfma_f32_16x16x32_bf16 v[98:101], v[184:187], v[214:217], v[98:101]
	v_mfma_f32_16x16x32_bf16 v[86:89], v[176:179], v[222:225], v[86:89]
	v_mfma_f32_16x16x32_bf16 v[82:85], v[184:187], v[222:225], v[82:85]
	v_mfma_f32_16x16x32_bf16 v[68:71], v[176:179], v[230:233], v[68:71]
	v_mfma_f32_16x16x32_bf16 v[64:67], v[184:187], v[230:233], v[64:67]
	s_barrier
	s_setprio 0
	s_add_i32 s65, s65, s46
	v_lshl_add_u64 v[140:141], s[24:25], 0, v[80:81]
	s_mov_b32 m0, s65
	ds_read_b128 v[202:205], v146 offset:16384
	ds_read_b128 v[206:209], v146 offset:17408
	ds_read_b128 v[210:213], v146 offset:18432
	ds_read_b128 v[214:217], v146 offset:19456
	ds_read_b128 v[218:221], v146 offset:20480
	ds_read_b128 v[222:225], v146 offset:21504
	ds_read_b128 v[226:229], v146 offset:22528
	ds_read_b128 v[230:233], v146 offset:23552
	global_load_lds_dwordx4 v[140:141], off
	s_add_i32 m0, s65, 0x2000
	s_add_u32 s66, s24, 0x40000
	v_lshl_add_u64 v[152:153], s[24:25], 0, v[134:135]
	s_addc_u32 s67, s25, 0
	s_add_i32 s65, s68, s46
	global_load_lds_dwordx4 v[152:153], off
	v_lshl_add_u64 v[188:189], s[66:67], 0, v[80:81]
	s_mov_b32 m0, s65
	v_lshl_add_u64 v[196:197], s[26:27], 0, v[132:133]
	global_load_lds_dwordx4 v[188:189], off
	v_lshl_add_u64 v[188:189], s[66:67], 0, v[134:135]
	s_add_i32 m0, s65, 0x2000
	s_nop 0
	global_load_lds_dwordx4 v[188:189], off
	v_lshl_add_u64 v[188:189], s[26:27], 0, v[130:131]
	s_mov_b32 m0, s47
	s_nop 0
	global_load_lds_dwordx4 v[188:189], off
	s_mov_b32 m0, s48
	s_nop 0
	global_load_lds_dwordx4 v[196:197], off
	s_waitcnt vmcnt(8)
	s_waitcnt lgkmcnt(0)
	s_setprio 1
	s_barrier
; #define PG8_STAGE(bufoff, gbase, voff) do { _Pragma("unroll") for (int _i = 0; _i < 2; ++_i) \
;         __builtin_amdgcn_global_load_lds((const unsigned*)((const char*)(gbase) + (voff)[_i]), (PG8_LAS unsigned*)(lds + (bufoff) + ldsw + _i * 8192), 16, 0, 0); } while (0)
; #define PG8_LDA(dst, b, h) do { _Pragma("unroll") for (int m = 0; m < 4; ++m) _Pragma("unroll") for (int k = 0; k < 2; ++k) dst[m][k] = *(const PG8_LAS bf16x8*)(lds + PG8_SA(b, h) + aoff + m * 2048 + k * 1024); } while (0)
; #define PG8_LDB(dst, b, h) do { _Pragma("unroll") for (int n = 0; n < 2; ++n) _Pragma("unroll") for (int k = 0; k < 2; ++k) dst[n][k] = *(const PG8_LAS bf16x8*)(lds + PG8_SB(b, h) + boff + n * 2048 + k * 1024); } while (0)
; #define PG8_MMA(ai, bj, At, Bt) do { __builtin_amdgcn_s_setprio(1); _Pragma("unroll") for (int m = 0; m < 4; ++m) _Pragma("unroll") for (int n = 0; n < 2; ++n) _Pragma("unroll") for (int k = 0; k < 2; ++k) \
;         acc[ai][bj][m][n] = __builtin_amdgcn_mfma_f32_16x16x32_bf16(Bt[n][k], At[m][k], acc[ai][bj][m][n], 0, 0, 0); __builtin_amdgcn_s_setprio(0); } while (0)
; #define PG8_WAIT_V(n) asm volatile("s_waitcnt vmcnt(" #n ")" ::: "memory")
; #define PG8_WAIT_L(n) asm volatile("s_waitcnt lgkmcnt(" #n ")" ::: "memory")
; #define PG8_BAR __builtin_amdgcn_s_barrier()
; #define PG8_SCHED __builtin_amdgcn_sched_barrier(0)
; template <class Epi, class Sched, bool ALIGN_EPI = false, bool SP2 = false, bool HALFM = false>
; __device__ __forceinline__ void gemm_phase(PG8_LAS unsigned char* lds, const Gemm g, const Sched& S, const Epi& E) {
;     ...
;             PG8_WAIT_V(8); PG8_WAIT_L(0); PG8_BAR; if constexpr (!HALFM) { PG8_MMA(1, 0, At, B0); PG8_MMA(1, 1, At, B1); } PG8_BAR; PG8_SCHED;
;             PG8_LDB(B0, 1, 0); PG8_LDB(B1, 1, 1); PG8_SCHED; PG8_LDA(At, 1, 0); PG8_STAGE(PG8_SA(0, 1), a2 + hstep, voffA);
;             PG8_WAIT_V(8); PG8_WAIT_L(0); PG8_BAR; PG8_MMA(0, 0, At, B0); PG8_MMA(0, 1, At, B1); PG8_BAR; PG8_SCHED;
	v_mfma_f32_16x16x32_bf16 v[60:63], v[148:151], v[202:205], v[60:63]
	v_mfma_f32_16x16x32_bf16 v[56:59], v[164:167], v[202:205], v[56:59]
	v_mfma_f32_16x16x32_bf16 v[44:47], v[148:151], v[210:213], v[44:47]
	v_mfma_f32_16x16x32_bf16 v[40:43], v[164:167], v[210:213], v[40:43]
	v_mfma_f32_16x16x32_bf16 v[28:31], v[148:151], v[218:221], v[28:31]
	v_mfma_f32_16x16x32_bf16 v[24:27], v[164:167], v[218:221], v[24:27]
	v_mfma_f32_16x16x32_bf16 v[12:15], v[148:151], v[226:229], v[12:15]
	v_mfma_f32_16x16x32_bf16 v[8:11], v[164:167], v[226:229], v[8:11]
	v_mfma_f32_16x16x32_bf16 v[60:63], v[160:163], v[206:209], v[60:63]
	v_mfma_f32_16x16x32_bf16 v[56:59], v[168:171], v[206:209], v[56:59]
	v_mfma_f32_16x16x32_bf16 v[44:47], v[160:163], v[214:217], v[44:47]
	v_mfma_f32_16x16x32_bf16 v[40:43], v[168:171], v[214:217], v[40:43]
	v_mfma_f32_16x16x32_bf16 v[28:31], v[160:163], v[222:225], v[28:31]
	v_mfma_f32_16x16x32_bf16 v[24:27], v[168:171], v[222:225], v[24:27]
	v_mfma_f32_16x16x32_bf16 v[12:15], v[160:163], v[230:233], v[12:15]
	v_mfma_f32_16x16x32_bf16 v[8:11], v[168:171], v[230:233], v[8:11]
	v_mfma_f32_16x16x32_bf16 v[52:55], v[172:175], v[202:205], v[52:55]
	v_mfma_f32_16x16x32_bf16 v[48:51], v[180:183], v[202:205], v[48:51]
	v_mfma_f32_16x16x32_bf16 v[36:39], v[172:175], v[210:213], v[36:39]
	v_mfma_f32_16x16x32_bf16 v[32:35], v[180:183], v[210:213], v[32:35]
	v_mfma_f32_16x16x32_bf16 v[20:23], v[172:175], v[218:221], v[20:23]
	v_mfma_f32_16x16x32_bf16 v[16:19], v[180:183], v[218:221], v[16:19]
	v_mfma_f32_16x16x32_bf16 v[4:7], v[172:175], v[226:229], v[4:7]
	v_mfma_f32_16x16x32_bf16 v[0:3], v[180:183], v[226:229], v[0:3]
	v_mfma_f32_16x16x32_bf16 v[52:55], v[176:179], v[206:209], v[52:55]
	v_mfma_f32_16x16x32_bf16 v[48:51], v[184:187], v[206:209], v[48:51]
	v_mfma_f32_16x16x32_bf16 v[36:39], v[176:179], v[214:217], v[36:39]
	v_mfma_f32_16x16x32_bf16 v[32:35], v[184:187], v[214:217], v[32:35]
	v_mfma_f32_16x16x32_bf16 v[20:23], v[176:179], v[222:225], v[20:23]
	v_mfma_f32_16x16x32_bf16 v[16:19], v[184:187], v[222:225], v[16:19]
	v_mfma_f32_16x16x32_bf16 v[4:7], v[176:179], v[230:233], v[4:7]
	v_mfma_f32_16x16x32_bf16 v[0:3], v[184:187], v[230:233], v[0:3]
	s_barrier
	s_setprio 0
	s_add_i32 s65, 0, 0x18000
	v_add_u32_e32 v147, s65, v143
	s_add_i32 s66, 0, 0x1c000
	ds_read_b128 v[148:151], v147
	ds_read_b128 v[160:163], v147 offset:1024
	ds_read_b128 v[164:167], v147 offset:2048
	ds_read_b128 v[168:171], v147 offset:3072
	v_add_u32_e32 v147, s66, v143
	ds_read_b128 v[172:175], v147
	ds_read_b128 v[176:179], v147 offset:1024
	ds_read_b128 v[180:183], v147 offset:2048
	ds_read_b128 v[184:187], v147 offset:3072
	s_add_u32 s26, s26, 0x40000
	s_addc_u32 s27, s27, 0
	s_mov_b32 m0, s49
	v_lshl_add_u64 v[198:199], s[26:27], 0, v[130:131]
	ds_read_b128 v[202:205], v146 offset:32768
	ds_read_b128 v[206:209], v146 offset:33792
	ds_read_b128 v[210:213], v146 offset:34816
	ds_read_b128 v[214:217], v146 offset:35840
	ds_read_b128 v[218:221], v146 offset:36864
	ds_read_b128 v[222:225], v146 offset:37888
	ds_read_b128 v[226:229], v146 offset:38912
	ds_read_b128 v[230:233], v146 offset:39936
	global_load_lds_dwordx4 v[198:199], off
	v_lshl_add_u64 v[198:199], s[26:27], 0, v[132:133]
	s_mov_b32 m0, s50
	s_nop 0
	global_load_lds_dwordx4 v[198:199], off
	s_waitcnt vmcnt(8)
	s_waitcnt lgkmcnt(0)
	s_setprio 1
	s_barrier
	v_mfma_f32_16x16x32_bf16 v[126:129], v[148:151], v[202:205], v[126:129]
	v_mfma_f32_16x16x32_bf16 v[122:125], v[164:167], v[202:205], v[122:125]
	v_mfma_f32_16x16x32_bf16 v[110:113], v[148:151], v[210:213], v[110:113]
	v_mfma_f32_16x16x32_bf16 v[106:109], v[164:167], v[210:213], v[106:109]
	v_mfma_f32_16x16x32_bf16 v[94:97], v[148:151], v[218:221], v[94:97]
	v_mfma_f32_16x16x32_bf16 v[90:93], v[164:167], v[218:221], v[90:93]
	v_mfma_f32_16x16x32_bf16 v[76:79], v[148:151], v[226:229], v[76:79]
	v_mfma_f32_16x16x32_bf16 v[72:75], v[164:167], v[226:229], v[72:75]
	v_mfma_f32_16x16x32_bf16 v[126:129], v[160:163], v[206:209], v[126:129]
	v_mfma_f32_16x16x32_bf16 v[122:125], v[168:171], v[206:209], v[122:125]
	v_mfma_f32_16x16x32_bf16 v[110:113], v[160:163], v[214:217], v[110:113]
	v_mfma_f32_16x16x32_bf16 v[106:109], v[168:171], v[214:217], v[106:109]
	v_mfma_f32_16x16x32_bf16 v[94:97], v[160:163], v[222:225], v[94:97]
	v_mfma_f32_16x16x32_bf16 v[90:93], v[168:171], v[222:225], v[90:93]
	v_mfma_f32_16x16x32_bf16 v[76:79], v[160:163], v[230:233], v[76:79]
	v_mfma_f32_16x16x32_bf16 v[72:75], v[168:171], v[230:233], v[72:75]
	v_mfma_f32_16x16x32_bf16 v[118:121], v[172:175], v[202:205], v[118:121]
	v_mfma_f32_16x16x32_bf16 v[114:117], v[180:183], v[202:205], v[114:117]
	v_mfma_f32_16x16x32_bf16 v[102:105], v[172:175], v[210:213], v[102:105]
	v_mfma_f32_16x16x32_bf16 v[98:101], v[180:183], v[210:213], v[98:101]
	v_mfma_f32_16x16x32_bf16 v[86:89], v[172:175], v[218:221], v[86:89]
	v_mfma_f32_16x16x32_bf16 v[82:85], v[180:183], v[218:221], v[82:85]
	v_mfma_f32_16x16x32_bf16 v[68:71], v[172:175], v[226:229], v[68:71]
	v_mfma_f32_16x16x32_bf16 v[64:67], v[180:183], v[226:229], v[64:67]
	v_mfma_f32_16x16x32_bf16 v[118:121], v[176:179], v[206:209], v[118:121]
	v_mfma_f32_16x16x32_bf16 v[114:117], v[184:187], v[206:209], v[114:117]
	v_mfma_f32_16x16x32_bf16 v[102:105], v[176:179], v[214:217], v[102:105]
	v_mfma_f32_16x16x32_bf16 v[98:101], v[184:187], v[214:217], v[98:101]
	v_mfma_f32_16x16x32_bf16 v[86:89], v[176:179], v[222:225], v[86:89]
	v_mfma_f32_16x16x32_bf16 v[82:85], v[184:187], v[222:225], v[82:85]
	v_mfma_f32_16x16x32_bf16 v[68:71], v[176:179], v[230:233], v[68:71]
	v_mfma_f32_16x16x32_bf16 v[64:67], v[184:187], v[230:233], v[64:67]
	s_barrier
; #define PG8_STAGE(bufoff, gbase, voff) do { _Pragma("unroll") for (int _i = 0; _i < 2; ++_i) \
;         __builtin_amdgcn_global_load_lds((const unsigned*)((const char*)(gbase) + (voff)[_i]), (PG8_LAS unsigned*)(lds + (bufoff) + ldsw + _i * 8192), 16, 0, 0); } while (0)
; #define PG8_LDA(dst, b, h) do { _Pragma("unroll") for (int m = 0; m < 4; ++m) _Pragma("unroll") for (int k = 0; k < 2; ++k) dst[m][k] = *(const PG8_LAS bf16x8*)(lds + PG8_SA(b, h) + aoff + m * 2048 + k * 1024); } while (0)
; #define PG8_MMA(ai, bj, At, Bt) do { __builtin_amdgcn_s_setprio(1); _Pragma("unroll") for (int m = 0; m < 4; ++m) _Pragma("unroll") for (int n = 0; n < 2; ++n) _Pragma("unroll") for (int k = 0; k < 2; ++k) \
;         acc[ai][bj][m][n] = __builtin_amdgcn_mfma_f32_16x16x32_bf16(Bt[n][k], At[m][k], acc[ai][bj][m][n], 0, 0, 0); __builtin_amdgcn_s_setprio(0); } while (0)
; #define PG8_WAIT_V(n) asm volatile("s_waitcnt vmcnt(" #n ")" ::: "memory")
; #define PG8_WAIT_L(n) asm volatile("s_waitcnt lgkmcnt(" #n ")" ::: "memory")
; #define PG8_BAR __builtin_amdgcn_s_barrier()
; #define PG8_SCHED __builtin_amdgcn_sched_barrier(0)
; template <class Epi, class Sched, bool ALIGN_EPI = false, bool SP2 = false, bool HALFM = false>
; __device__ __forceinline__ void gemm_phase(PG8_LAS unsigned char* lds, const Gemm g, const Sched& S, const Epi& E) {
;     ...
;             PG8_WAIT_V(8); PG8_WAIT_L(0); PG8_BAR; PG8_MMA(0, 0, At, B0); PG8_MMA(0, 1, At, B1); PG8_BAR; PG8_SCHED;
;             if constexpr (!HALFM) PG8_LDA(At, 1, 1); PG8_STAGE(PG8_SB(1, 0), b3, voffB); PG8_STAGE(PG8_SB(1, 1), b3 + hstep, voffB); PG8_STAGE(PG8_SA(1, 0), a3, voffA);
;             PG8_WAIT_V(8); PG8_WAIT_L(0); PG8_BAR; if constexpr (!HALFM) { PG8_MMA(1, 0, At, B0); PG8_MMA(1, 1, At, B1); } PG8_BAR; PG8_SCHED;
	s_setprio 0
	s_add_i32 s26, s65, s46
	v_lshl_add_u64 v[140:141], v[140:141], 0, s[82:83]
	s_mov_b32 m0, s26
	ds_read_b128 v[202:205], v146 offset:49152
	ds_read_b128 v[206:209], v146 offset:50176
	ds_read_b128 v[210:213], v146 offset:51200
	ds_read_b128 v[214:217], v146 offset:52224
	ds_read_b128 v[218:221], v146 offset:53248
	ds_read_b128 v[222:225], v146 offset:54272
	ds_read_b128 v[226:229], v146 offset:55296
	ds_read_b128 v[230:233], v146 offset:56320
	global_load_lds_dwordx4 v[140:141], off
	s_add_i32 m0, s26, 0x2000
	s_add_u32 s24, s24, 0x40080
	v_lshl_add_u64 v[140:141], v[152:153], 0, s[82:83]
	s_addc_u32 s25, s25, 0
	s_add_i32 s26, s66, s46
	global_load_lds_dwordx4 v[140:141], off
	v_lshl_add_u64 v[140:141], s[24:25], 0, v[80:81]
	s_mov_b32 m0, s26
	s_nop 0
	global_load_lds_dwordx4 v[140:141], off
	v_lshl_add_u64 v[140:141], s[24:25], 0, v[134:135]
	s_add_i32 m0, s26, 0x2000
	s_nop 0
	global_load_lds_dwordx4 v[140:141], off
	v_lshl_add_u64 v[140:141], v[188:189], 0, s[82:83]
	s_mov_b32 m0, s51
	s_nop 0
	global_load_lds_dwordx4 v[140:141], off
	v_lshl_add_u64 v[140:141], v[196:197], 0, s[82:83]
	s_mov_b32 m0, s52
	s_nop 0
	global_load_lds_dwordx4 v[140:141], off
	s_waitcnt vmcnt(8)
	s_waitcnt lgkmcnt(0)
	s_setprio 1
	s_barrier
	v_mfma_f32_16x16x32_bf16 v[60:63], v[148:151], v[202:205], v[60:63]
	v_mfma_f32_16x16x32_bf16 v[56:59], v[164:167], v[202:205], v[56:59]
	v_mfma_f32_16x16x32_bf16 v[44:47], v[148:151], v[210:213], v[44:47]
	v_mfma_f32_16x16x32_bf16 v[40:43], v[164:167], v[210:213], v[40:43]
	v_mfma_f32_16x16x32_bf16 v[28:31], v[148:151], v[218:221], v[28:31]
	v_mfma_f32_16x16x32_bf16 v[24:27], v[164:167], v[218:221], v[24:27]
	v_mfma_f32_16x16x32_bf16 v[12:15], v[148:151], v[226:229], v[12:15]
	v_mfma_f32_16x16x32_bf16 v[8:11], v[164:167], v[226:229], v[8:11]
	v_mfma_f32_16x16x32_bf16 v[60:63], v[160:163], v[206:209], v[60:63]
	v_mfma_f32_16x16x32_bf16 v[56:59], v[168:171], v[206:209], v[56:59]
	v_mfma_f32_16x16x32_bf16 v[44:47], v[160:163], v[214:217], v[44:47]
	v_mfma_f32_16x16x32_bf16 v[40:43], v[168:171], v[214:217], v[40:43]
	v_mfma_f32_16x16x32_bf16 v[28:31], v[160:163], v[222:225], v[28:31]
	v_mfma_f32_16x16x32_bf16 v[24:27], v[168:171], v[222:225], v[24:27]
	v_mfma_f32_16x16x32_bf16 v[12:15], v[160:163], v[230:233], v[12:15]
	v_mfma_f32_16x16x32_bf16 v[8:11], v[168:171], v[230:233], v[8:11]
	v_mfma_f32_16x16x32_bf16 v[52:55], v[172:175], v[202:205], v[52:55]
	v_mfma_f32_16x16x32_bf16 v[48:51], v[180:183], v[202:205], v[48:51]
	v_mfma_f32_16x16x32_bf16 v[36:39], v[172:175], v[210:213], v[36:39]
	v_mfma_f32_16x16x32_bf16 v[32:35], v[180:183], v[210:213], v[32:35]
	v_mfma_f32_16x16x32_bf16 v[20:23], v[172:175], v[218:221], v[20:23]
	v_mfma_f32_16x16x32_bf16 v[16:19], v[180:183], v[218:221], v[16:19]
	v_mfma_f32_16x16x32_bf16 v[4:7], v[172:175], v[226:229], v[4:7]
	v_mfma_f32_16x16x32_bf16 v[0:3], v[180:183], v[226:229], v[0:3]
	v_mfma_f32_16x16x32_bf16 v[52:55], v[176:179], v[206:209], v[52:55]
	v_mfma_f32_16x16x32_bf16 v[48:51], v[184:187], v[206:209], v[48:51]
	v_mfma_f32_16x16x32_bf16 v[36:39], v[176:179], v[214:217], v[36:39]
	v_mfma_f32_16x16x32_bf16 v[32:35], v[184:187], v[214:217], v[32:35]
	v_mfma_f32_16x16x32_bf16 v[20:23], v[176:179], v[222:225], v[20:23]
	v_mfma_f32_16x16x32_bf16 v[16:19], v[184:187], v[222:225], v[16:19]
	v_mfma_f32_16x16x32_bf16 v[4:7], v[176:179], v[230:233], v[4:7]
	v_mfma_f32_16x16x32_bf16 v[0:3], v[184:187], v[230:233], v[0:3]
	s_barrier
	s_setprio 0
	s_add_i32 s64, s64, 2
	s_add_u32 s22, s22, 0x100
	s_addc_u32 s23, s23, 0
	s_add_u32 s62, s62, 0x100
	s_addc_u32 s63, s63, 0
	s_cmp_gt_u32 s64, 13
	s_cbranch_scc1 .LBB0_183

; #define PG8_STAGE(bufoff, gbase, voff) do { _Pragma("unroll") for (int _i = 0; _i < 2; ++_i) \
;         __builtin_amdgcn_global_load_lds((const unsigned*)((const char*)(gbase) + (voff)[_i]), (PG8_LAS unsigned*)(lds + (bufoff) + ldsw + _i * 8192), 16, 0, 0); } while (0)
; #define PG8_LDA(dst, b, h) do { _Pragma("unroll") for (int m = 0; m < 4; ++m) _Pragma("unroll") for (int k = 0; k < 2; ++k) dst[m][k] = *(const PG8_LAS bf16x8*)(lds + PG8_SA(b, h) + aoff + m * 2048 + k * 1024); } while (0)
; #define PG8_LDB(dst, b, h) do { _Pragma("unroll") for (int n = 0; n < 2; ++n) _Pragma("unroll") for (int k = 0; k < 2; ++k) dst[n][k] = *(const PG8_LAS bf16x8*)(lds + PG8_SB(b, h) + boff + n * 2048 + k * 1024); } while (0)
; #define PG8_MMA(ai, bj, At, Bt) do { __builtin_amdgcn_s_setprio(1); _Pragma("unroll") for (int m = 0; m < 4; ++m) _Pragma("unroll") for (int n = 0; n < 2; ++n) _Pragma("unroll") for (int k = 0; k < 2; ++k) \
;         acc[ai][bj][m][n] = __builtin_amdgcn_mfma_f32_16x16x32_bf16(Bt[n][k], At[m][k], acc[ai][bj][m][n], 0, 0, 0); __builtin_amdgcn_s_setprio(0); } while (0)
; #define PG8_WAIT_V(n) asm volatile("s_waitcnt vmcnt(" #n ")" ::: "memory")
; #define PG8_WAIT_L(n) asm volatile("s_waitcnt lgkmcnt(" #n ")" ::: "memory")
; #define PG8_BAR __builtin_amdgcn_s_barrier()
; #define PG8_SCHED __builtin_amdgcn_sched_barrier(0)
; template <class Epi, class Sched, bool ALIGN_EPI = false, bool SP2 = false, bool HALFM = false>
; __device__ __forceinline__ void gemm_phase(PG8_LAS unsigned char* lds, const Gemm g, const Sched& S, const Epi& E) {
;     ...
;             PG8_LDB(B0, 0, 0); PG8_LDB(B1, 0, 1); PG8_SCHED; PG8_LDA(At, 0, 0); PG8_STAGE(PG8_SA(1, 1), a1 + hstep, voffA);
;             PG8_WAIT_V(8); PG8_WAIT_L(0); PG8_BAR; PG8_MMA(0, 0, At, B0); PG8_MMA(0, 1, At, B1); PG8_BAR; PG8_SCHED;
;             if constexpr (!HALFM) PG8_LDA(At, 0, 1); PG8_STAGE(PG8_SB(0, 0), b2, voffB); PG8_STAGE(PG8_SB(0, 1), b2 + hstep, voffB); PG8_STAGE(PG8_SA(0, 0), a2, voffA);
;             PG8_WAIT_V(8); PG8_WAIT_L(0); PG8_BAR; if constexpr (!HALFM) { PG8_MMA(1, 0, At, B0); PG8_MMA(1, 1, At, B1); } PG8_BAR; PG8_SCHED;
.LBB0_274:
	s_add_u32 s22, s20, 0x100
	s_addc_u32 s23, s21, 0
	s_add_i32 s61, 0, 0x10000
	s_cmp_eq_u32 s60, 40
	s_cselect_b32 s27, s17, s23
	s_cselect_b32 s26, s16, s22
	s_cselect_b32 s25, s19, s59
	s_cselect_b32 s24, s18, s58
	s_add_i32 s62, 0, 0x14000
	v_add_u32_e32 v142, s61, v203
	v_add_u32_e32 v174, s62, v203
	ds_read_b128 v[130:133], v142
	ds_read_b128 v[134:137], v142 offset:1024
	ds_read_b128 v[138:141], v142 offset:2048
	ds_read_b128 v[142:145], v142 offset:3072
	ds_read_b128 v[146:149], v174
	ds_read_b128 v[150:153], v174 offset:1024
	ds_read_b128 v[170:173], v174 offset:2048
	ds_read_b128 v[174:177], v174 offset:3072
	v_lshl_add_u64 v[196:197], s[20:21], 0, v[166:167]
	s_add_i32 m0, s46, 0xc000
	ds_read_b128 v[178:181], v205
	ds_read_b128 v[182:185], v205 offset:1024
	ds_read_b128 v[186:189], v205 offset:2048
	ds_read_b128 v[206:209], v205 offset:3072
	ds_read_b128 v[210:213], v205 offset:4096
	ds_read_b128 v[214:217], v205 offset:5120
	ds_read_b128 v[218:221], v205 offset:6144
	ds_read_b128 v[222:225], v205 offset:7168
	global_load_lds_dwordx4 v[196:197], off
	v_lshl_add_u64 v[196:197], s[20:21], 0, v[168:169]
	s_add_i32 m0, s46, 0xe000
	s_nop 0
	global_load_lds_dwordx4 v[196:197], off
	s_waitcnt vmcnt(8)
	s_waitcnt lgkmcnt(0)
	s_setprio 1
	s_barrier
	v_mfma_f32_16x16x32_bf16 v[126:129], v[130:133], v[178:181], v[126:129]
	v_mfma_f32_16x16x32_bf16 v[122:125], v[138:141], v[178:181], v[122:125]
	v_mfma_f32_16x16x32_bf16 v[110:113], v[130:133], v[186:189], v[110:113]
	v_mfma_f32_16x16x32_bf16 v[106:109], v[138:141], v[186:189], v[106:109]
	v_mfma_f32_16x16x32_bf16 v[94:97], v[130:133], v[210:213], v[94:97]
	v_mfma_f32_16x16x32_bf16 v[90:93], v[138:141], v[210:213], v[90:93]
	v_mfma_f32_16x16x32_bf16 v[76:79], v[130:133], v[218:221], v[76:79]
	v_mfma_f32_16x16x32_bf16 v[72:75], v[138:141], v[218:221], v[72:75]
	v_mfma_f32_16x16x32_bf16 v[126:129], v[134:137], v[182:185], v[126:129]
	v_mfma_f32_16x16x32_bf16 v[122:125], v[142:145], v[182:185], v[122:125]
	v_mfma_f32_16x16x32_bf16 v[110:113], v[134:137], v[206:209], v[110:113]
	v_mfma_f32_16x16x32_bf16 v[106:109], v[142:145], v[206:209], v[106:109]
	v_mfma_f32_16x16x32_bf16 v[94:97], v[134:137], v[214:217], v[94:97]
	v_mfma_f32_16x16x32_bf16 v[90:93], v[142:145], v[214:217], v[90:93]
	v_mfma_f32_16x16x32_bf16 v[76:79], v[134:137], v[222:225], v[76:79]
	v_mfma_f32_16x16x32_bf16 v[72:75], v[142:145], v[222:225], v[72:75]
	v_mfma_f32_16x16x32_bf16 v[118:121], v[146:149], v[178:181], v[118:121]
	v_mfma_f32_16x16x32_bf16 v[114:117], v[170:173], v[178:181], v[114:117]
	v_mfma_f32_16x16x32_bf16 v[102:105], v[146:149], v[186:189], v[102:105]
	v_mfma_f32_16x16x32_bf16 v[98:101], v[170:173], v[186:189], v[98:101]
	v_mfma_f32_16x16x32_bf16 v[86:89], v[146:149], v[210:213], v[86:89]
	v_mfma_f32_16x16x32_bf16 v[82:85], v[170:173], v[210:213], v[82:85]
	v_mfma_f32_16x16x32_bf16 v[68:71], v[146:149], v[218:221], v[68:71]
	v_mfma_f32_16x16x32_bf16 v[64:67], v[170:173], v[218:221], v[64:67]
	v_mfma_f32_16x16x32_bf16 v[118:121], v[150:153], v[182:185], v[118:121]
	v_mfma_f32_16x16x32_bf16 v[114:117], v[174:177], v[182:185], v[114:117]
	v_mfma_f32_16x16x32_bf16 v[102:105], v[150:153], v[206:209], v[102:105]
	v_mfma_f32_16x16x32_bf16 v[98:101], v[174:177], v[206:209], v[98:101]
	v_mfma_f32_16x16x32_bf16 v[86:89], v[150:153], v[214:217], v[86:89]
	v_mfma_f32_16x16x32_bf16 v[82:85], v[174:177], v[214:217], v[82:85]
	v_mfma_f32_16x16x32_bf16 v[68:71], v[150:153], v[222:225], v[68:71]
	v_mfma_f32_16x16x32_bf16 v[64:67], v[174:177], v[222:225], v[64:67]
	s_barrier
	s_setprio 0
	s_add_i32 s20, s61, s28
	v_lshl_add_u64 v[196:197], s[24:25], 0, v[80:81]
	s_mov_b32 m0, s20
	ds_read_b128 v[178:181], v205 offset:16384
	ds_read_b128 v[182:185], v205 offset:17408
	ds_read_b128 v[186:189], v205 offset:18432
	ds_read_b128 v[206:209], v205 offset:19456
	ds_read_b128 v[210:213], v205 offset:20480
	ds_read_b128 v[214:217], v205 offset:21504
	ds_read_b128 v[218:221], v205 offset:22528
	ds_read_b128 v[222:225], v205 offset:23552
	global_load_lds_dwordx4 v[196:197], off
	s_add_i32 m0, s20, 0x2000
	s_add_u32 s20, s24, 0xb0000
	v_lshl_add_u64 v[198:199], s[24:25], 0, v[160:161]
	s_addc_u32 s21, s25, 0
	s_add_i32 s61, s62, s28
	global_load_lds_dwordx4 v[198:199], off
	v_lshl_add_u64 v[226:227], s[20:21], 0, v[80:81]
	s_mov_b32 m0, s61
	v_lshl_add_u64 v[228:229], s[26:27], 0, v[162:163]
	global_load_lds_dwordx4 v[226:227], off
	v_lshl_add_u64 v[226:227], s[20:21], 0, v[160:161]
	s_add_i32 m0, s61, 0x2000
	s_nop 0
	global_load_lds_dwordx4 v[226:227], off
	v_lshl_add_u64 v[226:227], s[26:27], 0, v[164:165]
	s_mov_b32 m0, s46
	s_nop 0
	global_load_lds_dwordx4 v[226:227], off
	s_mov_b32 m0, s47
	s_nop 0
	global_load_lds_dwordx4 v[228:229], off
	s_waitcnt vmcnt(8)
	s_waitcnt lgkmcnt(0)
	s_setprio 1
	s_barrier
; #define PG8_STAGE(bufoff, gbase, voff) do { _Pragma("unroll") for (int _i = 0; _i < 2; ++_i) \
;         __builtin_amdgcn_global_load_lds((const unsigned*)((const char*)(gbase) + (voff)[_i]), (PG8_LAS unsigned*)(lds + (bufoff) + ldsw + _i * 8192), 16, 0, 0); } while (0)
; #define PG8_LDA(dst, b, h) do { _Pragma("unroll") for (int m = 0; m < 4; ++m) _Pragma("unroll") for (int k = 0; k < 2; ++k) dst[m][k] = *(const PG8_LAS bf16x8*)(lds + PG8_SA(b, h) + aoff + m * 2048 + k * 1024); } while (0)
; #define PG8_LDB(dst, b, h) do { _Pragma("unroll") for (int n = 0; n < 2; ++n) _Pragma("unroll") for (int k = 0; k < 2; ++k) dst[n][k] = *(const PG8_LAS bf16x8*)(lds + PG8_SB(b, h) + boff + n * 2048 + k * 1024); } while (0)
; #define PG8_MMA(ai, bj, At, Bt) do { __builtin_amdgcn_s_setprio(1); _Pragma("unroll") for (int m = 0; m < 4; ++m) _Pragma("unroll") for (int n = 0; n < 2; ++n) _Pragma("unroll") for (int k = 0; k < 2; ++k) \
;         acc[ai][bj][m][n] = __builtin_amdgcn_mfma_f32_16x16x32_bf16(Bt[n][k], At[m][k], acc[ai][bj][m][n], 0, 0, 0); __builtin_amdgcn_s_setprio(0); } while (0)
; #define PG8_WAIT_V(n) asm volatile("s_waitcnt vmcnt(" #n ")" ::: "memory")
; #define PG8_WAIT_L(n) asm volatile("s_waitcnt lgkmcnt(" #n ")" ::: "memory")
; #define PG8_BAR __builtin_amdgcn_s_barrier()
; #define PG8_SCHED __builtin_amdgcn_sched_barrier(0)
; template <class Epi, class Sched, bool ALIGN_EPI = false, bool SP2 = false, bool HALFM = false>
; __device__ __forceinline__ void gemm_phase(PG8_LAS unsigned char* lds, const Gemm g, const Sched& S, const Epi& E) {
;     ...
;             PG8_WAIT_V(8); PG8_WAIT_L(0); PG8_BAR; if constexpr (!HALFM) { PG8_MMA(1, 0, At, B0); PG8_MMA(1, 1, At, B1); } PG8_BAR; PG8_SCHED;
;             PG8_LDB(B0, 1, 0); PG8_LDB(B1, 1, 1); PG8_SCHED; PG8_LDA(At, 1, 0); PG8_STAGE(PG8_SA(0, 1), a2 + hstep, voffA);
;             PG8_WAIT_V(8); PG8_WAIT_L(0); PG8_BAR; PG8_MMA(0, 0, At, B0); PG8_MMA(0, 1, At, B1); PG8_BAR; PG8_SCHED;
	v_mfma_f32_16x16x32_bf16 v[60:63], v[130:133], v[178:181], v[60:63]
	v_mfma_f32_16x16x32_bf16 v[56:59], v[138:141], v[178:181], v[56:59]
	v_mfma_f32_16x16x32_bf16 v[44:47], v[130:133], v[186:189], v[44:47]
	v_mfma_f32_16x16x32_bf16 v[40:43], v[138:141], v[186:189], v[40:43]
	v_mfma_f32_16x16x32_bf16 v[28:31], v[130:133], v[210:213], v[28:31]
	v_mfma_f32_16x16x32_bf16 v[24:27], v[138:141], v[210:213], v[24:27]
	v_mfma_f32_16x16x32_bf16 v[12:15], v[130:133], v[218:221], v[12:15]
	v_mfma_f32_16x16x32_bf16 v[8:11], v[138:141], v[218:221], v[8:11]
	v_mfma_f32_16x16x32_bf16 v[60:63], v[134:137], v[182:185], v[60:63]
	v_mfma_f32_16x16x32_bf16 v[56:59], v[142:145], v[182:185], v[56:59]
	v_mfma_f32_16x16x32_bf16 v[44:47], v[134:137], v[206:209], v[44:47]
	v_mfma_f32_16x16x32_bf16 v[40:43], v[142:145], v[206:209], v[40:43]
	v_mfma_f32_16x16x32_bf16 v[28:31], v[134:137], v[214:217], v[28:31]
	v_mfma_f32_16x16x32_bf16 v[24:27], v[142:145], v[214:217], v[24:27]
	v_mfma_f32_16x16x32_bf16 v[12:15], v[134:137], v[222:225], v[12:15]
	v_mfma_f32_16x16x32_bf16 v[8:11], v[142:145], v[222:225], v[8:11]
	v_mfma_f32_16x16x32_bf16 v[52:55], v[146:149], v[178:181], v[52:55]
	v_mfma_f32_16x16x32_bf16 v[48:51], v[170:173], v[178:181], v[48:51]
	v_mfma_f32_16x16x32_bf16 v[36:39], v[146:149], v[186:189], v[36:39]
	v_mfma_f32_16x16x32_bf16 v[32:35], v[170:173], v[186:189], v[32:35]
	v_mfma_f32_16x16x32_bf16 v[20:23], v[146:149], v[210:213], v[20:23]
	v_mfma_f32_16x16x32_bf16 v[16:19], v[170:173], v[210:213], v[16:19]
	v_mfma_f32_16x16x32_bf16 v[4:7], v[146:149], v[218:221], v[4:7]
	v_mfma_f32_16x16x32_bf16 v[0:3], v[170:173], v[218:221], v[0:3]
	v_mfma_f32_16x16x32_bf16 v[52:55], v[150:153], v[182:185], v[52:55]
	v_mfma_f32_16x16x32_bf16 v[48:51], v[174:177], v[182:185], v[48:51]
	v_mfma_f32_16x16x32_bf16 v[36:39], v[150:153], v[206:209], v[36:39]
	v_mfma_f32_16x16x32_bf16 v[32:35], v[174:177], v[206:209], v[32:35]
	v_mfma_f32_16x16x32_bf16 v[20:23], v[150:153], v[214:217], v[20:23]
	v_mfma_f32_16x16x32_bf16 v[16:19], v[174:177], v[214:217], v[16:19]
	v_mfma_f32_16x16x32_bf16 v[4:7], v[150:153], v[222:225], v[4:7]
	v_mfma_f32_16x16x32_bf16 v[0:3], v[174:177], v[222:225], v[0:3]
	s_barrier
	s_setprio 0
	s_add_i32 s61, 0, 0x18000
	s_add_i32 s62, 0, 0x1c000
	v_add_u32_e32 v142, s61, v203
	v_add_u32_e32 v174, s62, v203
	ds_read_b128 v[130:133], v142
	ds_read_b128 v[134:137], v142 offset:1024
	ds_read_b128 v[138:141], v142 offset:2048
	ds_read_b128 v[142:145], v142 offset:3072
	ds_read_b128 v[146:149], v174
	ds_read_b128 v[150:153], v174 offset:1024
	ds_read_b128 v[170:173], v174 offset:2048
	ds_read_b128 v[174:177], v174 offset:3072
	s_add_u32 s20, s26, 0xb0000
	s_addc_u32 s21, s27, 0
	s_mov_b32 m0, s48
	v_lshl_add_u64 v[230:231], s[20:21], 0, v[164:165]
	ds_read_b128 v[178:181], v205 offset:32768
	ds_read_b128 v[182:185], v205 offset:33792
	ds_read_b128 v[186:189], v205 offset:34816
	ds_read_b128 v[206:209], v205 offset:35840
	ds_read_b128 v[210:213], v205 offset:36864
	ds_read_b128 v[214:217], v205 offset:37888
	ds_read_b128 v[218:221], v205 offset:38912
	ds_read_b128 v[222:225], v205 offset:39936
	global_load_lds_dwordx4 v[230:231], off
	v_lshl_add_u64 v[230:231], s[20:21], 0, v[162:163]
	s_mov_b32 m0, s49
	s_nop 0
	global_load_lds_dwordx4 v[230:231], off
	s_waitcnt vmcnt(8)
	s_waitcnt lgkmcnt(0)
	s_setprio 1
	s_barrier
	v_mfma_f32_16x16x32_bf16 v[126:129], v[130:133], v[178:181], v[126:129]
	v_mfma_f32_16x16x32_bf16 v[122:125], v[138:141], v[178:181], v[122:125]
	v_mfma_f32_16x16x32_bf16 v[110:113], v[130:133], v[186:189], v[110:113]
	v_mfma_f32_16x16x32_bf16 v[106:109], v[138:141], v[186:189], v[106:109]
	v_mfma_f32_16x16x32_bf16 v[94:97], v[130:133], v[210:213], v[94:97]
	v_mfma_f32_16x16x32_bf16 v[90:93], v[138:141], v[210:213], v[90:93]
	v_mfma_f32_16x16x32_bf16 v[76:79], v[130:133], v[218:221], v[76:79]
	v_mfma_f32_16x16x32_bf16 v[72:75], v[138:141], v[218:221], v[72:75]
	v_mfma_f32_16x16x32_bf16 v[126:129], v[134:137], v[182:185], v[126:129]
	v_mfma_f32_16x16x32_bf16 v[122:125], v[142:145], v[182:185], v[122:125]
	v_mfma_f32_16x16x32_bf16 v[110:113], v[134:137], v[206:209], v[110:113]
	v_mfma_f32_16x16x32_bf16 v[106:109], v[142:145], v[206:209], v[106:109]
	v_mfma_f32_16x16x32_bf16 v[94:97], v[134:137], v[214:217], v[94:97]
	v_mfma_f32_16x16x32_bf16 v[90:93], v[142:145], v[214:217], v[90:93]
	v_mfma_f32_16x16x32_bf16 v[76:79], v[134:137], v[222:225], v[76:79]
	v_mfma_f32_16x16x32_bf16 v[72:75], v[142:145], v[222:225], v[72:75]
	v_mfma_f32_16x16x32_bf16 v[118:121], v[146:149], v[178:181], v[118:121]
	v_mfma_f32_16x16x32_bf16 v[114:117], v[170:173], v[178:181], v[114:117]
	v_mfma_f32_16x16x32_bf16 v[102:105], v[146:149], v[186:189], v[102:105]
	v_mfma_f32_16x16x32_bf16 v[98:101], v[170:173], v[186:189], v[98:101]
	v_mfma_f32_16x16x32_bf16 v[86:89], v[146:149], v[210:213], v[86:89]
	v_mfma_f32_16x16x32_bf16 v[82:85], v[170:173], v[210:213], v[82:85]
	v_mfma_f32_16x16x32_bf16 v[68:71], v[146:149], v[218:221], v[68:71]
	v_mfma_f32_16x16x32_bf16 v[64:67], v[170:173], v[218:221], v[64:67]
	v_mfma_f32_16x16x32_bf16 v[118:121], v[150:153], v[182:185], v[118:121]
	v_mfma_f32_16x16x32_bf16 v[114:117], v[174:177], v[182:185], v[114:117]
	v_mfma_f32_16x16x32_bf16 v[102:105], v[150:153], v[206:209], v[102:105]
	v_mfma_f32_16x16x32_bf16 v[98:101], v[174:177], v[206:209], v[98:101]
	v_mfma_f32_16x16x32_bf16 v[86:89], v[150:153], v[214:217], v[86:89]
	v_mfma_f32_16x16x32_bf16 v[82:85], v[174:177], v[214:217], v[82:85]
	v_mfma_f32_16x16x32_bf16 v[68:71], v[150:153], v[222:225], v[68:71]
	v_mfma_f32_16x16x32_bf16 v[64:67], v[174:177], v[222:225], v[64:67]
	s_barrier
; #define PG8_STAGE(bufoff, gbase, voff) do { _Pragma("unroll") for (int _i = 0; _i < 2; ++_i) \
;         __builtin_amdgcn_global_load_lds((const unsigned*)((const char*)(gbase) + (voff)[_i]), (PG8_LAS unsigned*)(lds + (bufoff) + ldsw + _i * 8192), 16, 0, 0); } while (0)
; #define PG8_LDA(dst, b, h) do { _Pragma("unroll") for (int m = 0; m < 4; ++m) _Pragma("unroll") for (int k = 0; k < 2; ++k) dst[m][k] = *(const PG8_LAS bf16x8*)(lds + PG8_SA(b, h) + aoff + m * 2048 + k * 1024); } while (0)
; #define PG8_MMA(ai, bj, At, Bt) do { __builtin_amdgcn_s_setprio(1); _Pragma("unroll") for (int m = 0; m < 4; ++m) _Pragma("unroll") for (int n = 0; n < 2; ++n) _Pragma("unroll") for (int k = 0; k < 2; ++k) \
;         acc[ai][bj][m][n] = __builtin_amdgcn_mfma_f32_16x16x32_bf16(Bt[n][k], At[m][k], acc[ai][bj][m][n], 0, 0, 0); __builtin_amdgcn_s_setprio(0); } while (0)
; #define PG8_WAIT_V(n) asm volatile("s_waitcnt vmcnt(" #n ")" ::: "memory")
; #define PG8_WAIT_L(n) asm volatile("s_waitcnt lgkmcnt(" #n ")" ::: "memory")
; #define PG8_BAR __builtin_amdgcn_s_barrier()
; #define PG8_SCHED __builtin_amdgcn_sched_barrier(0)
; template <class Epi, class Sched, bool ALIGN_EPI = false, bool SP2 = false, bool HALFM = false>
; __device__ __forceinline__ void gemm_phase(PG8_LAS unsigned char* lds, const Gemm g, const Sched& S, const Epi& E) {
;     ...
;             PG8_WAIT_V(8); PG8_WAIT_L(0); PG8_BAR; PG8_MMA(0, 0, At, B0); PG8_MMA(0, 1, At, B1); PG8_BAR; PG8_SCHED;
;             if constexpr (!HALFM) PG8_LDA(At, 1, 1); PG8_STAGE(PG8_SB(1, 0), b3, voffB); PG8_STAGE(PG8_SB(1, 1), b3 + hstep, voffB); PG8_STAGE(PG8_SA(1, 0), a3, voffA);
;             PG8_WAIT_V(8); PG8_WAIT_L(0); PG8_BAR; if constexpr (!HALFM) { PG8_MMA(1, 0, At, B0); PG8_MMA(1, 1, At, B1); } PG8_BAR; PG8_SCHED;
	s_setprio 0
	s_add_i32 s20, s61, s28
	v_lshl_add_u64 v[196:197], v[196:197], 0, s[82:83]
	s_mov_b32 m0, s20
	ds_read_b128 v[178:181], v205 offset:49152
	ds_read_b128 v[182:185], v205 offset:50176
	ds_read_b128 v[186:189], v205 offset:51200
	ds_read_b128 v[206:209], v205 offset:52224
	ds_read_b128 v[210:213], v205 offset:53248
	ds_read_b128 v[214:217], v205 offset:54272
	ds_read_b128 v[218:221], v205 offset:55296
	ds_read_b128 v[222:225], v205 offset:56320
	global_load_lds_dwordx4 v[196:197], off
	s_add_i32 m0, s20, 0x2000
	s_add_u32 s20, s24, 0xb0080
	v_lshl_add_u64 v[196:197], v[198:199], 0, s[82:83]
	s_addc_u32 s21, s25, 0
	s_add_i32 s24, s62, s28
	global_load_lds_dwordx4 v[196:197], off
	v_lshl_add_u64 v[196:197], s[20:21], 0, v[80:81]
	s_mov_b32 m0, s24
	s_nop 0
	global_load_lds_dwordx4 v[196:197], off
	v_lshl_add_u64 v[196:197], s[20:21], 0, v[160:161]
	s_add_i32 m0, s24, 0x2000
	s_nop 0
	global_load_lds_dwordx4 v[196:197], off
	v_lshl_add_u64 v[196:197], v[226:227], 0, s[82:83]
	s_mov_b32 m0, s52
	s_nop 0
	global_load_lds_dwordx4 v[196:197], off
	v_lshl_add_u64 v[196:197], v[228:229], 0, s[82:83]
	s_mov_b32 m0, s53
	s_nop 0
	global_load_lds_dwordx4 v[196:197], off
	s_waitcnt vmcnt(8)
	s_waitcnt lgkmcnt(0)
	s_setprio 1
	s_barrier
	v_mfma_f32_16x16x32_bf16 v[60:63], v[130:133], v[178:181], v[60:63]
	v_mfma_f32_16x16x32_bf16 v[56:59], v[138:141], v[178:181], v[56:59]
	v_mfma_f32_16x16x32_bf16 v[44:47], v[130:133], v[186:189], v[44:47]
	v_mfma_f32_16x16x32_bf16 v[40:43], v[138:141], v[186:189], v[40:43]
	v_mfma_f32_16x16x32_bf16 v[28:31], v[130:133], v[210:213], v[28:31]
	v_mfma_f32_16x16x32_bf16 v[24:27], v[138:141], v[210:213], v[24:27]
	v_mfma_f32_16x16x32_bf16 v[12:15], v[130:133], v[218:221], v[12:15]
	v_mfma_f32_16x16x32_bf16 v[8:11], v[138:141], v[218:221], v[8:11]
	v_mfma_f32_16x16x32_bf16 v[60:63], v[134:137], v[182:185], v[60:63]
	v_mfma_f32_16x16x32_bf16 v[56:59], v[142:145], v[182:185], v[56:59]
	v_mfma_f32_16x16x32_bf16 v[44:47], v[134:137], v[206:209], v[44:47]
	v_mfma_f32_16x16x32_bf16 v[40:43], v[142:145], v[206:209], v[40:43]
	v_mfma_f32_16x16x32_bf16 v[28:31], v[134:137], v[214:217], v[28:31]
	v_mfma_f32_16x16x32_bf16 v[24:27], v[142:145], v[214:217], v[24:27]
	v_mfma_f32_16x16x32_bf16 v[12:15], v[134:137], v[222:225], v[12:15]
	v_mfma_f32_16x16x32_bf16 v[8:11], v[142:145], v[222:225], v[8:11]
	v_mfma_f32_16x16x32_bf16 v[52:55], v[146:149], v[178:181], v[52:55]
	v_mfma_f32_16x16x32_bf16 v[48:51], v[170:173], v[178:181], v[48:51]
	v_mfma_f32_16x16x32_bf16 v[36:39], v[146:149], v[186:189], v[36:39]
	v_mfma_f32_16x16x32_bf16 v[32:35], v[170:173], v[186:189], v[32:35]
	v_mfma_f32_16x16x32_bf16 v[20:23], v[146:149], v[210:213], v[20:23]
	v_mfma_f32_16x16x32_bf16 v[16:19], v[170:173], v[210:213], v[16:19]
	v_mfma_f32_16x16x32_bf16 v[4:7], v[146:149], v[218:221], v[4:7]
	v_mfma_f32_16x16x32_bf16 v[0:3], v[170:173], v[218:221], v[0:3]
	v_mfma_f32_16x16x32_bf16 v[52:55], v[150:153], v[182:185], v[52:55]
	v_mfma_f32_16x16x32_bf16 v[48:51], v[174:177], v[182:185], v[48:51]
	v_mfma_f32_16x16x32_bf16 v[36:39], v[150:153], v[206:209], v[36:39]
	v_mfma_f32_16x16x32_bf16 v[32:35], v[174:177], v[206:209], v[32:35]
	v_mfma_f32_16x16x32_bf16 v[20:23], v[150:153], v[214:217], v[20:23]
	v_mfma_f32_16x16x32_bf16 v[16:19], v[174:177], v[214:217], v[16:19]
	v_mfma_f32_16x16x32_bf16 v[4:7], v[150:153], v[222:225], v[4:7]
	v_mfma_f32_16x16x32_bf16 v[0:3], v[174:177], v[222:225], v[0:3]
	s_barrier
	s_setprio 0
	s_add_i32 s60, s60, 2
	s_add_u32 s58, s58, 0x100
	s_addc_u32 s59, s59, 0
	s_cmp_gt_u32 s60, 41
	s_mov_b64 s[20:21], s[22:23]
	s_cbranch_scc0 .LBB0_274
	s_and_b64 vcc, exec, s[12:13]
	s_cbranch_vccz .LBB0_277
	s_barrier

; #define PG8_STAGE(bufoff, gbase, voff) do { _Pragma("unroll") for (int _i = 0; _i < 2; ++_i) \
;         __builtin_amdgcn_global_load_lds((const unsigned*)((const char*)(gbase) + (voff)[_i]), (PG8_LAS unsigned*)(lds + (bufoff) + ldsw + _i * 8192), 16, 0, 0); } while (0)
; #define PG8_LDA(dst, b, h) do { _Pragma("unroll") for (int m = 0; m < 4; ++m) _Pragma("unroll") for (int k = 0; k < 2; ++k) dst[m][k] = *(const PG8_LAS bf16x8*)(lds + PG8_SA(b, h) + aoff + m * 2048 + k * 1024); } while (0)
; #define PG8_LDB(dst, b, h) do { _Pragma("unroll") for (int n = 0; n < 2; ++n) _Pragma("unroll") for (int k = 0; k < 2; ++k) dst[n][k] = *(const PG8_LAS bf16x8*)(lds + PG8_SB(b, h) + boff + n * 2048 + k * 1024); } while (0)
; #define PG8_MMA(ai, bj, At, Bt) do { __builtin_amdgcn_s_setprio(1); _Pragma("unroll") for (int m = 0; m < 4; ++m) _Pragma("unroll") for (int n = 0; n < 2; ++n) _Pragma("unroll") for (int k = 0; k < 2; ++k) \
;         acc[ai][bj][m][n] = __builtin_amdgcn_mfma_f32_16x16x32_bf16(Bt[n][k], At[m][k], acc[ai][bj][m][n], 0, 0, 0); __builtin_amdgcn_s_setprio(0); } while (0)
; #define PG8_WAIT_V(n) asm volatile("s_waitcnt vmcnt(" #n ")" ::: "memory")
; #define PG8_WAIT_L(n) asm volatile("s_waitcnt lgkmcnt(" #n ")" ::: "memory")
; #define PG8_BAR __builtin_amdgcn_s_barrier()
; #define PG8_SCHED __builtin_amdgcn_sched_barrier(0)
; template <class Epi, class Sched, bool ALIGN_EPI = false, bool SP2 = false, bool HALFM = false>
; __device__ __forceinline__ void gemm_phase(PG8_LAS unsigned char* lds, const Gemm g, const Sched& S, const Epi& E) {
;     ...
;             PG8_LDB(B0, 0, 0); PG8_LDB(B1, 0, 1); PG8_SCHED; PG8_LDA(At, 0, 0); PG8_STAGE(PG8_SA(1, 1), a1 + hstep, voffA);
;             PG8_WAIT_V(8); PG8_WAIT_L(0); PG8_BAR; PG8_MMA(0, 0, At, B0); PG8_MMA(0, 1, At, B1); PG8_BAR; PG8_SCHED;
;             if constexpr (!HALFM) PG8_LDA(At, 0, 1); PG8_STAGE(PG8_SB(0, 0), b2, voffB); PG8_STAGE(PG8_SB(0, 1), b2 + hstep, voffB); PG8_STAGE(PG8_SA(0, 0), a2, voffA);
;             PG8_WAIT_V(8); PG8_WAIT_L(0); PG8_BAR; if constexpr (!HALFM) { PG8_MMA(1, 0, At, B0); PG8_MMA(1, 1, At, B1); } PG8_BAR; PG8_SCHED;
.LBB0_413:
	s_add_u32 s28, s24, 0xfffc0080
	s_addc_u32 s29, s25, -1
	s_and_b64 s[26:27], s[26:27], exec
	s_cselect_b32 s29, s29, s15
	s_cselect_b32 s28, s28, s60
	s_cselect_b32 s27, s65, s13
	s_cselect_b32 s26, s64, s61
	s_add_i32 s67, 0, 0x10000
	s_add_i32 s70, 0, 0x14000
	v_add_u32_e32 v142, s67, v179
	v_add_u32_e32 v183, s70, v179
	ds_read_b128 v[130:133], v142
	ds_read_b128 v[134:137], v142 offset:1024
	ds_read_b128 v[138:141], v142 offset:2048
	ds_read_b128 v[142:145], v142 offset:3072
	ds_read_b128 v[166:169], v183
	ds_read_b128 v[170:173], v183 offset:1024
	ds_read_b128 v[174:177], v183 offset:2048
	ds_read_b128 v[184:187], v183 offset:3072
	v_lshl_add_u64 v[188:189], s[24:25], 0, v[162:163]
	s_add_i32 m0, s49, 0xc000
	ds_read_b128 v[202:205], v182
	ds_read_b128 v[206:209], v182 offset:1024
	ds_read_b128 v[210:213], v182 offset:2048
	ds_read_b128 v[214:217], v182 offset:3072
	ds_read_b128 v[218:221], v182 offset:4096
	ds_read_b128 v[222:225], v182 offset:5120
	ds_read_b128 v[226:229], v182 offset:6144
	ds_read_b128 v[230:233], v182 offset:7168
	global_load_lds_dwordx4 v[188:189], off
	v_lshl_add_u64 v[188:189], s[24:25], 0, v[164:165]
	s_add_i32 m0, s49, 0xe000
	s_nop 0
	global_load_lds_dwordx4 v[188:189], off
	s_waitcnt vmcnt(8)
	s_waitcnt lgkmcnt(0)
	s_setprio 1
	s_barrier
	v_mfma_f32_16x16x32_bf16 v[126:129], v[130:133], v[202:205], v[126:129]
	v_mfma_f32_16x16x32_bf16 v[122:125], v[138:141], v[202:205], v[122:125]
	v_mfma_f32_16x16x32_bf16 v[110:113], v[130:133], v[210:213], v[110:113]
	v_mfma_f32_16x16x32_bf16 v[106:109], v[138:141], v[210:213], v[106:109]
	v_mfma_f32_16x16x32_bf16 v[94:97], v[130:133], v[218:221], v[94:97]
	v_mfma_f32_16x16x32_bf16 v[90:93], v[138:141], v[218:221], v[90:93]
	v_mfma_f32_16x16x32_bf16 v[76:79], v[130:133], v[226:229], v[76:79]
	v_mfma_f32_16x16x32_bf16 v[72:75], v[138:141], v[226:229], v[72:75]
	v_mfma_f32_16x16x32_bf16 v[126:129], v[134:137], v[206:209], v[126:129]
	v_mfma_f32_16x16x32_bf16 v[122:125], v[142:145], v[206:209], v[122:125]
	v_mfma_f32_16x16x32_bf16 v[110:113], v[134:137], v[214:217], v[110:113]
	v_mfma_f32_16x16x32_bf16 v[106:109], v[142:145], v[214:217], v[106:109]
	v_mfma_f32_16x16x32_bf16 v[94:97], v[134:137], v[222:225], v[94:97]
	v_mfma_f32_16x16x32_bf16 v[90:93], v[142:145], v[222:225], v[90:93]
	v_mfma_f32_16x16x32_bf16 v[76:79], v[134:137], v[230:233], v[76:79]
	v_mfma_f32_16x16x32_bf16 v[72:75], v[142:145], v[230:233], v[72:75]
	v_mfma_f32_16x16x32_bf16 v[118:121], v[166:169], v[202:205], v[118:121]
	v_mfma_f32_16x16x32_bf16 v[114:117], v[174:177], v[202:205], v[114:117]
	v_mfma_f32_16x16x32_bf16 v[102:105], v[166:169], v[210:213], v[102:105]
	v_mfma_f32_16x16x32_bf16 v[98:101], v[174:177], v[210:213], v[98:101]
	v_mfma_f32_16x16x32_bf16 v[86:89], v[166:169], v[218:221], v[86:89]
	v_mfma_f32_16x16x32_bf16 v[82:85], v[174:177], v[218:221], v[82:85]
	v_mfma_f32_16x16x32_bf16 v[68:71], v[166:169], v[226:229], v[68:71]
	v_mfma_f32_16x16x32_bf16 v[64:67], v[174:177], v[226:229], v[64:67]
	v_mfma_f32_16x16x32_bf16 v[118:121], v[170:173], v[206:209], v[118:121]
	v_mfma_f32_16x16x32_bf16 v[114:117], v[184:187], v[206:209], v[114:117]
	v_mfma_f32_16x16x32_bf16 v[102:105], v[170:173], v[214:217], v[102:105]
	v_mfma_f32_16x16x32_bf16 v[98:101], v[184:187], v[214:217], v[98:101]
	v_mfma_f32_16x16x32_bf16 v[86:89], v[170:173], v[222:225], v[86:89]
	v_mfma_f32_16x16x32_bf16 v[82:85], v[184:187], v[222:225], v[82:85]
	v_mfma_f32_16x16x32_bf16 v[68:71], v[170:173], v[230:233], v[68:71]
	v_mfma_f32_16x16x32_bf16 v[64:67], v[184:187], v[230:233], v[64:67]
	s_barrier
	s_setprio 0
	s_add_i32 s67, s67, s48
	v_lshl_add_u64 v[188:189], s[26:27], 0, v[80:81]
	s_mov_b32 m0, s67
	ds_read_b128 v[202:205], v182 offset:16384
	ds_read_b128 v[206:209], v182 offset:17408
	ds_read_b128 v[210:213], v182 offset:18432
	ds_read_b128 v[214:217], v182 offset:19456
	ds_read_b128 v[218:221], v182 offset:20480
	ds_read_b128 v[222:225], v182 offset:21504
	ds_read_b128 v[226:229], v182 offset:22528
	ds_read_b128 v[230:233], v182 offset:23552
	global_load_lds_dwordx4 v[188:189], off
	s_add_i32 m0, s67, 0x2000
	s_add_u32 s68, s26, 0x40000
	v_lshl_add_u64 v[196:197], s[26:27], 0, v[150:151]
	s_addc_u32 s69, s27, 0
	s_add_i32 s67, s70, s48
	global_load_lds_dwordx4 v[196:197], off
	v_lshl_add_u64 v[198:199], s[68:69], 0, v[80:81]
	s_mov_b32 m0, s67
	v_lshl_add_u64 v[234:235], s[28:29], 0, v[148:149]
	global_load_lds_dwordx4 v[198:199], off
	v_lshl_add_u64 v[198:199], s[68:69], 0, v[150:151]
	s_add_i32 m0, s67, 0x2000
	s_nop 0
	global_load_lds_dwordx4 v[198:199], off
	v_lshl_add_u64 v[198:199], s[28:29], 0, v[146:147]
	s_mov_b32 m0, s49
	s_nop 0
	global_load_lds_dwordx4 v[198:199], off
	s_mov_b32 m0, s50
	s_nop 0
	global_load_lds_dwordx4 v[234:235], off
	s_waitcnt vmcnt(8)
	s_waitcnt lgkmcnt(0)
	s_setprio 1
	s_barrier
; #define PG8_STAGE(bufoff, gbase, voff) do { _Pragma("unroll") for (int _i = 0; _i < 2; ++_i) \
;         __builtin_amdgcn_global_load_lds((const unsigned*)((const char*)(gbase) + (voff)[_i]), (PG8_LAS unsigned*)(lds + (bufoff) + ldsw + _i * 8192), 16, 0, 0); } while (0)
; #define PG8_LDA(dst, b, h) do { _Pragma("unroll") for (int m = 0; m < 4; ++m) _Pragma("unroll") for (int k = 0; k < 2; ++k) dst[m][k] = *(const PG8_LAS bf16x8*)(lds + PG8_SA(b, h) + aoff + m * 2048 + k * 1024); } while (0)
; #define PG8_LDB(dst, b, h) do { _Pragma("unroll") for (int n = 0; n < 2; ++n) _Pragma("unroll") for (int k = 0; k < 2; ++k) dst[n][k] = *(const PG8_LAS bf16x8*)(lds + PG8_SB(b, h) + boff + n * 2048 + k * 1024); } while (0)
; #define PG8_MMA(ai, bj, At, Bt) do { __builtin_amdgcn_s_setprio(1); _Pragma("unroll") for (int m = 0; m < 4; ++m) _Pragma("unroll") for (int n = 0; n < 2; ++n) _Pragma("unroll") for (int k = 0; k < 2; ++k) \
;         acc[ai][bj][m][n] = __builtin_amdgcn_mfma_f32_16x16x32_bf16(Bt[n][k], At[m][k], acc[ai][bj][m][n], 0, 0, 0); __builtin_amdgcn_s_setprio(0); } while (0)
; #define PG8_WAIT_V(n) asm volatile("s_waitcnt vmcnt(" #n ")" ::: "memory")
; #define PG8_WAIT_L(n) asm volatile("s_waitcnt lgkmcnt(" #n ")" ::: "memory")
; #define PG8_BAR __builtin_amdgcn_s_barrier()
; #define PG8_SCHED __builtin_amdgcn_sched_barrier(0)
; template <class Epi, class Sched, bool ALIGN_EPI = false, bool SP2 = false, bool HALFM = false>
; __device__ __forceinline__ void gemm_phase(PG8_LAS unsigned char* lds, const Gemm g, const Sched& S, const Epi& E) {
;     ...
;             PG8_WAIT_V(8); PG8_WAIT_L(0); PG8_BAR; if constexpr (!HALFM) { PG8_MMA(1, 0, At, B0); PG8_MMA(1, 1, At, B1); } PG8_BAR; PG8_SCHED;
;             PG8_LDB(B0, 1, 0); PG8_LDB(B1, 1, 1); PG8_SCHED; PG8_LDA(At, 1, 0); PG8_STAGE(PG8_SA(0, 1), a2 + hstep, voffA);
;             PG8_WAIT_V(8); PG8_WAIT_L(0); PG8_BAR; PG8_MMA(0, 0, At, B0); PG8_MMA(0, 1, At, B1); PG8_BAR; PG8_SCHED;
	v_mfma_f32_16x16x32_bf16 v[60:63], v[130:133], v[202:205], v[60:63]
	v_mfma_f32_16x16x32_bf16 v[56:59], v[138:141], v[202:205], v[56:59]
	v_mfma_f32_16x16x32_bf16 v[44:47], v[130:133], v[210:213], v[44:47]
	v_mfma_f32_16x16x32_bf16 v[40:43], v[138:141], v[210:213], v[40:43]
	v_mfma_f32_16x16x32_bf16 v[28:31], v[130:133], v[218:221], v[28:31]
	v_mfma_f32_16x16x32_bf16 v[24:27], v[138:141], v[218:221], v[24:27]
	v_mfma_f32_16x16x32_bf16 v[12:15], v[130:133], v[226:229], v[12:15]
	v_mfma_f32_16x16x32_bf16 v[8:11], v[138:141], v[226:229], v[8:11]
	v_mfma_f32_16x16x32_bf16 v[60:63], v[134:137], v[206:209], v[60:63]
	v_mfma_f32_16x16x32_bf16 v[56:59], v[142:145], v[206:209], v[56:59]
	v_mfma_f32_16x16x32_bf16 v[44:47], v[134:137], v[214:217], v[44:47]
	v_mfma_f32_16x16x32_bf16 v[40:43], v[142:145], v[214:217], v[40:43]
	v_mfma_f32_16x16x32_bf16 v[28:31], v[134:137], v[222:225], v[28:31]
	v_mfma_f32_16x16x32_bf16 v[24:27], v[142:145], v[222:225], v[24:27]
	v_mfma_f32_16x16x32_bf16 v[12:15], v[134:137], v[230:233], v[12:15]
	v_mfma_f32_16x16x32_bf16 v[8:11], v[142:145], v[230:233], v[8:11]
	v_mfma_f32_16x16x32_bf16 v[52:55], v[166:169], v[202:205], v[52:55]
	v_mfma_f32_16x16x32_bf16 v[48:51], v[174:177], v[202:205], v[48:51]
	v_mfma_f32_16x16x32_bf16 v[36:39], v[166:169], v[210:213], v[36:39]
	v_mfma_f32_16x16x32_bf16 v[32:35], v[174:177], v[210:213], v[32:35]
	v_mfma_f32_16x16x32_bf16 v[20:23], v[166:169], v[218:221], v[20:23]
	v_mfma_f32_16x16x32_bf16 v[16:19], v[174:177], v[218:221], v[16:19]
	v_mfma_f32_16x16x32_bf16 v[4:7], v[166:169], v[226:229], v[4:7]
	v_mfma_f32_16x16x32_bf16 v[0:3], v[174:177], v[226:229], v[0:3]
	v_mfma_f32_16x16x32_bf16 v[52:55], v[170:173], v[206:209], v[52:55]
	v_mfma_f32_16x16x32_bf16 v[48:51], v[184:187], v[206:209], v[48:51]
	v_mfma_f32_16x16x32_bf16 v[36:39], v[170:173], v[214:217], v[36:39]
	v_mfma_f32_16x16x32_bf16 v[32:35], v[184:187], v[214:217], v[32:35]
	v_mfma_f32_16x16x32_bf16 v[20:23], v[170:173], v[222:225], v[20:23]
	v_mfma_f32_16x16x32_bf16 v[16:19], v[184:187], v[222:225], v[16:19]
	v_mfma_f32_16x16x32_bf16 v[4:7], v[170:173], v[230:233], v[4:7]
	v_mfma_f32_16x16x32_bf16 v[0:3], v[184:187], v[230:233], v[0:3]
	s_barrier
	s_setprio 0
	s_add_i32 s67, 0, 0x18000
	s_add_i32 s68, 0, 0x1c000
	v_add_u32_e32 v142, s67, v179
	v_add_u32_e32 v183, s68, v179
	ds_read_b128 v[130:133], v142
	ds_read_b128 v[134:137], v142 offset:1024
	ds_read_b128 v[138:141], v142 offset:2048
	ds_read_b128 v[142:145], v142 offset:3072
	ds_read_b128 v[166:169], v183
	ds_read_b128 v[170:173], v183 offset:1024
	ds_read_b128 v[174:177], v183 offset:2048
	ds_read_b128 v[184:187], v183 offset:3072
	s_add_u32 s28, s28, 0x40000
	s_addc_u32 s29, s29, 0
	s_mov_b32 m0, s51
	v_lshl_add_u64 v[236:237], s[28:29], 0, v[146:147]
	ds_read_b128 v[202:205], v182 offset:32768
	ds_read_b128 v[206:209], v182 offset:33792
	ds_read_b128 v[210:213], v182 offset:34816
	ds_read_b128 v[214:217], v182 offset:35840
	ds_read_b128 v[218:221], v182 offset:36864
	ds_read_b128 v[222:225], v182 offset:37888
	ds_read_b128 v[226:229], v182 offset:38912
	ds_read_b128 v[230:233], v182 offset:39936
	global_load_lds_dwordx4 v[236:237], off
	v_lshl_add_u64 v[236:237], s[28:29], 0, v[148:149]
	s_mov_b32 m0, s52
	s_nop 0
	global_load_lds_dwordx4 v[236:237], off
	s_waitcnt vmcnt(8)
	s_waitcnt lgkmcnt(0)
	s_setprio 1
	s_barrier
	v_mfma_f32_16x16x32_bf16 v[126:129], v[130:133], v[202:205], v[126:129]
	v_mfma_f32_16x16x32_bf16 v[122:125], v[138:141], v[202:205], v[122:125]
	v_mfma_f32_16x16x32_bf16 v[110:113], v[130:133], v[210:213], v[110:113]
	v_mfma_f32_16x16x32_bf16 v[106:109], v[138:141], v[210:213], v[106:109]
	v_mfma_f32_16x16x32_bf16 v[94:97], v[130:133], v[218:221], v[94:97]
	v_mfma_f32_16x16x32_bf16 v[90:93], v[138:141], v[218:221], v[90:93]
	v_mfma_f32_16x16x32_bf16 v[76:79], v[130:133], v[226:229], v[76:79]
	v_mfma_f32_16x16x32_bf16 v[72:75], v[138:141], v[226:229], v[72:75]
	v_mfma_f32_16x16x32_bf16 v[126:129], v[134:137], v[206:209], v[126:129]
	v_mfma_f32_16x16x32_bf16 v[122:125], v[142:145], v[206:209], v[122:125]
	v_mfma_f32_16x16x32_bf16 v[110:113], v[134:137], v[214:217], v[110:113]
	v_mfma_f32_16x16x32_bf16 v[106:109], v[142:145], v[214:217], v[106:109]
	v_mfma_f32_16x16x32_bf16 v[94:97], v[134:137], v[222:225], v[94:97]
	v_mfma_f32_16x16x32_bf16 v[90:93], v[142:145], v[222:225], v[90:93]
	v_mfma_f32_16x16x32_bf16 v[76:79], v[134:137], v[230:233], v[76:79]
	v_mfma_f32_16x16x32_bf16 v[72:75], v[142:145], v[230:233], v[72:75]
	v_mfma_f32_16x16x32_bf16 v[118:121], v[166:169], v[202:205], v[118:121]
	v_mfma_f32_16x16x32_bf16 v[114:117], v[174:177], v[202:205], v[114:117]
	v_mfma_f32_16x16x32_bf16 v[102:105], v[166:169], v[210:213], v[102:105]
	v_mfma_f32_16x16x32_bf16 v[98:101], v[174:177], v[210:213], v[98:101]
	v_mfma_f32_16x16x32_bf16 v[86:89], v[166:169], v[218:221], v[86:89]
	v_mfma_f32_16x16x32_bf16 v[82:85], v[174:177], v[218:221], v[82:85]
	v_mfma_f32_16x16x32_bf16 v[68:71], v[166:169], v[226:229], v[68:71]
	v_mfma_f32_16x16x32_bf16 v[64:67], v[174:177], v[226:229], v[64:67]
	v_mfma_f32_16x16x32_bf16 v[118:121], v[170:173], v[206:209], v[118:121]
	v_mfma_f32_16x16x32_bf16 v[114:117], v[184:187], v[206:209], v[114:117]
	v_mfma_f32_16x16x32_bf16 v[102:105], v[170:173], v[214:217], v[102:105]
	v_mfma_f32_16x16x32_bf16 v[98:101], v[184:187], v[214:217], v[98:101]
	v_mfma_f32_16x16x32_bf16 v[86:89], v[170:173], v[222:225], v[86:89]
	v_mfma_f32_16x16x32_bf16 v[82:85], v[184:187], v[222:225], v[82:85]
	v_mfma_f32_16x16x32_bf16 v[68:71], v[170:173], v[230:233], v[68:71]
	v_mfma_f32_16x16x32_bf16 v[64:67], v[184:187], v[230:233], v[64:67]
	s_barrier
; #define PG8_STAGE(bufoff, gbase, voff) do { _Pragma("unroll") for (int _i = 0; _i < 2; ++_i) \
;         __builtin_amdgcn_global_load_lds((const unsigned*)((const char*)(gbase) + (voff)[_i]), (PG8_LAS unsigned*)(lds + (bufoff) + ldsw + _i * 8192), 16, 0, 0); } while (0)
; #define PG8_LDA(dst, b, h) do { _Pragma("unroll") for (int m = 0; m < 4; ++m) _Pragma("unroll") for (int k = 0; k < 2; ++k) dst[m][k] = *(const PG8_LAS bf16x8*)(lds + PG8_SA(b, h) + aoff + m * 2048 + k * 1024); } while (0)
; #define PG8_MMA(ai, bj, At, Bt) do { __builtin_amdgcn_s_setprio(1); _Pragma("unroll") for (int m = 0; m < 4; ++m) _Pragma("unroll") for (int n = 0; n < 2; ++n) _Pragma("unroll") for (int k = 0; k < 2; ++k) \
;         acc[ai][bj][m][n] = __builtin_amdgcn_mfma_f32_16x16x32_bf16(Bt[n][k], At[m][k], acc[ai][bj][m][n], 0, 0, 0); __builtin_amdgcn_s_setprio(0); } while (0)
; #define PG8_WAIT_V(n) asm volatile("s_waitcnt vmcnt(" #n ")" ::: "memory")
; #define PG8_WAIT_L(n) asm volatile("s_waitcnt lgkmcnt(" #n ")" ::: "memory")
; #define PG8_BAR __builtin_amdgcn_s_barrier()
; #define PG8_SCHED __builtin_amdgcn_sched_barrier(0)
; template <class Epi, class Sched, bool ALIGN_EPI = false, bool SP2 = false, bool HALFM = false>
; __device__ __forceinline__ void gemm_phase(PG8_LAS unsigned char* lds, const Gemm g, const Sched& S, const Epi& E) {
;     ...
;             PG8_WAIT_V(8); PG8_WAIT_L(0); PG8_BAR; PG8_MMA(0, 0, At, B0); PG8_MMA(0, 1, At, B1); PG8_BAR; PG8_SCHED;
;             if constexpr (!HALFM) PG8_LDA(At, 1, 1); PG8_STAGE(PG8_SB(1, 0), b3, voffB); PG8_STAGE(PG8_SB(1, 1), b3 + hstep, voffB); PG8_STAGE(PG8_SA(1, 0), a3, voffA);
;             PG8_WAIT_V(8); PG8_WAIT_L(0); PG8_BAR; if constexpr (!HALFM) { PG8_MMA(1, 0, At, B0); PG8_MMA(1, 1, At, B1); } PG8_BAR; PG8_SCHED;
	s_setprio 0
	s_add_i32 s28, s67, s48
	v_lshl_add_u64 v[188:189], v[188:189], 0, s[82:83]
	s_mov_b32 m0, s28
	ds_read_b128 v[202:205], v182 offset:49152
	ds_read_b128 v[206:209], v182 offset:50176
	ds_read_b128 v[210:213], v182 offset:51200
	ds_read_b128 v[214:217], v182 offset:52224
	ds_read_b128 v[218:221], v182 offset:53248
	ds_read_b128 v[222:225], v182 offset:54272
	ds_read_b128 v[226:229], v182 offset:55296
	ds_read_b128 v[230:233], v182 offset:56320
	global_load_lds_dwordx4 v[188:189], off
	s_add_i32 m0, s28, 0x2000
	s_add_u32 s26, s26, 0x40080
	v_lshl_add_u64 v[188:189], v[196:197], 0, s[82:83]
	s_addc_u32 s27, s27, 0
	s_add_i32 s28, s68, s48
	global_load_lds_dwordx4 v[188:189], off
	v_lshl_add_u64 v[188:189], s[26:27], 0, v[80:81]
	s_mov_b32 m0, s28
	s_nop 0
	global_load_lds_dwordx4 v[188:189], off
	v_lshl_add_u64 v[188:189], s[26:27], 0, v[150:151]
	s_add_i32 m0, s28, 0x2000
	s_nop 0
	global_load_lds_dwordx4 v[188:189], off
	v_lshl_add_u64 v[188:189], v[198:199], 0, s[82:83]
	s_mov_b32 m0, s53
	s_nop 0
	global_load_lds_dwordx4 v[188:189], off
	v_lshl_add_u64 v[188:189], v[234:235], 0, s[82:83]
	s_mov_b32 m0, s54
	s_nop 0
	global_load_lds_dwordx4 v[188:189], off
	s_waitcnt vmcnt(8)
	s_waitcnt lgkmcnt(0)
	s_setprio 1
	s_barrier
	v_mfma_f32_16x16x32_bf16 v[60:63], v[130:133], v[202:205], v[60:63]
	v_mfma_f32_16x16x32_bf16 v[56:59], v[138:141], v[202:205], v[56:59]
	v_mfma_f32_16x16x32_bf16 v[44:47], v[130:133], v[210:213], v[44:47]
	v_mfma_f32_16x16x32_bf16 v[40:43], v[138:141], v[210:213], v[40:43]
	v_mfma_f32_16x16x32_bf16 v[28:31], v[130:133], v[218:221], v[28:31]
	v_mfma_f32_16x16x32_bf16 v[24:27], v[138:141], v[218:221], v[24:27]
	v_mfma_f32_16x16x32_bf16 v[12:15], v[130:133], v[226:229], v[12:15]
	v_mfma_f32_16x16x32_bf16 v[8:11], v[138:141], v[226:229], v[8:11]
	v_mfma_f32_16x16x32_bf16 v[60:63], v[134:137], v[206:209], v[60:63]
	v_mfma_f32_16x16x32_bf16 v[56:59], v[142:145], v[206:209], v[56:59]
	v_mfma_f32_16x16x32_bf16 v[44:47], v[134:137], v[214:217], v[44:47]
	v_mfma_f32_16x16x32_bf16 v[40:43], v[142:145], v[214:217], v[40:43]
	v_mfma_f32_16x16x32_bf16 v[28:31], v[134:137], v[222:225], v[28:31]
	v_mfma_f32_16x16x32_bf16 v[24:27], v[142:145], v[222:225], v[24:27]
	v_mfma_f32_16x16x32_bf16 v[12:15], v[134:137], v[230:233], v[12:15]
	v_mfma_f32_16x16x32_bf16 v[8:11], v[142:145], v[230:233], v[8:11]
	v_mfma_f32_16x16x32_bf16 v[52:55], v[166:169], v[202:205], v[52:55]
	v_mfma_f32_16x16x32_bf16 v[48:51], v[174:177], v[202:205], v[48:51]
	v_mfma_f32_16x16x32_bf16 v[36:39], v[166:169], v[210:213], v[36:39]
	v_mfma_f32_16x16x32_bf16 v[32:35], v[174:177], v[210:213], v[32:35]
	v_mfma_f32_16x16x32_bf16 v[20:23], v[166:169], v[218:221], v[20:23]
	v_mfma_f32_16x16x32_bf16 v[16:19], v[174:177], v[218:221], v[16:19]
	v_mfma_f32_16x16x32_bf16 v[4:7], v[166:169], v[226:229], v[4:7]
	v_mfma_f32_16x16x32_bf16 v[0:3], v[174:177], v[226:229], v[0:3]
	v_mfma_f32_16x16x32_bf16 v[52:55], v[170:173], v[206:209], v[52:55]
	v_mfma_f32_16x16x32_bf16 v[48:51], v[184:187], v[206:209], v[48:51]
	v_mfma_f32_16x16x32_bf16 v[36:39], v[170:173], v[214:217], v[36:39]
	v_mfma_f32_16x16x32_bf16 v[32:35], v[184:187], v[214:217], v[32:35]
	v_mfma_f32_16x16x32_bf16 v[20:23], v[170:173], v[222:225], v[20:23]
	v_mfma_f32_16x16x32_bf16 v[16:19], v[184:187], v[222:225], v[16:19]
	v_mfma_f32_16x16x32_bf16 v[4:7], v[170:173], v[230:233], v[4:7]
	v_mfma_f32_16x16x32_bf16 v[0:3], v[184:187], v[230:233], v[0:3]
	s_barrier
	s_setprio 0
	s_add_i32 s66, s66, 2
	s_add_u32 s24, s24, 0x100
	s_addc_u32 s25, s25, 0
	s_add_u32 s64, s64, 0x100
	s_addc_u32 s65, s65, 0
	s_cmp_gt_u32 s66, 13
	s_cbranch_scc1 .LBB0_417

; __device__ __forceinline__ unsigned cvt_pk_bf16(float lo, float hi) { unsigned r; asm volatile("v_cvt_pk_bf16_f32 %0, %1, %2" : "=v"(r) : "v"(lo), "v"(hi)); return r; }
; #define LAS __attribute__((address_space(3)))
; __device__ __forceinline__ int crow(int r, int hi) { return (r & 3) + 8 * (r >> 2) + 4 * hi; }
; template <bool MERGE> __device__ __forceinline__ void compute_b(LAS unsigned char* lds, const UD& x, unsigned char* ws, unsigned char* dout, int wid, int lane, const u32x4 (&pw)[10], float mx, float lsum) {
;     ...
;     LAS float* wsf = (LAS float*)(lds + L_WS + wid * 256);
;     LAS bf16_t* stg = (LAS bf16_t*)(lds + L_OST + wid * 4096);
;     if (hi == 0) {
;         wsf[r32] = lsum;
;         if (MERGE) wsf[32 + r32] = mx;
;         else { float* st = (float*)(ws + WS_STAT) + (((size_t)x.br * M + qtok) * NH + x.h) * 2; st[0] = mx; st[1] = lsum; }
;     }
;     asm volatile("s_waitcnt lgkmcnt(0)" ::: "memory");
; #pragma unroll
;     for (int r = 0; r < 16; ++r) {
;         const int qrow = crow(r, hi); const float rl = __builtin_amdgcn_rcpf(wsf[qrow]);
;         const unsigned a = pg8::cvt_pk_bf16(o[0][r] * rl, o[1][r] * rl);
;         stg[qrow * 64 + r32] = (bf16_t)(a & 0xffffu); stg[qrow * 64 + 32 + r32] = (bf16_t)(a >> 16);
;     }
;     asm volatile("s_waitcnt lgkmcnt(0)" ::: "memory");
;     if (!MERGE) {
;         bf16_t* Ob = o_base(ws, dout, x.br, x.b);
; #pragma unroll
;         for (int i = 0; i < 4; ++i) {
;             const int row = i * 8 + (lane >> 3), ch = lane & 7;
;             const u32x4 v = *(const LAS u32x4*)(stg + row * 64 + ch * 8);
;             *(u32x4*)(Ob + (tokb + (size_t)(t0 + row) * d + cls) * AW + x.h * HD + ch * 8) = v;
;         }
.LBB0_633:
	s_or_b64 exec, exec, vcc
	s_waitcnt lgkmcnt(0)
	ds_read_b32 v32, v165
	ds_read_b32 v33, v165 offset:4
	ds_read_b32 v34, v165 offset:8
	ds_read_b32 v35, v165 offset:12
	ds_read_b32 v36, v165 offset:32
	ds_read_b32 v37, v165 offset:36
	ds_read_b32 v38, v165 offset:40
	ds_read_b32 v39, v165 offset:44
	ds_read_b32 v40, v165 offset:64
	ds_read_b32 v41, v165 offset:68
	ds_read_b32 v42, v165 offset:72
	ds_read_b32 v43, v165 offset:76
	ds_read_b32 v44, v165 offset:96
	ds_read_b32 v45, v165 offset:100
	ds_read_b32 v46, v165 offset:104
	ds_read_b32 v47, v165 offset:108
	s_waitcnt lgkmcnt(0)
	s_and_b64 s[4:5], s[22:23], exec
	s_mov_b32 s4, 0x1800000
	s_cselect_b32 s0, 1, s0
	s_cselect_b32 s4, s4, 0x500000
	v_rcp_f32_e32 v32, v32
	v_readlane_b32 s18, v254, 59
	v_readlane_b32 s5, v253, 38
	v_readlane_b32 s19, v254, 60
	v_mul_f32_e32 v0, v0, v32
	v_mul_f32_e32 v16, v16, v32
	v_cvt_pk_bf16_f32 v0, v0, v16
	ds_write_b16 v166, v0
	ds_write_b16_d16_hi v167, v0
	s_mul_hi_i32 s13, s4, s0
	s_mul_i32 s4, s4, s0
	s_cselect_b32 s5, s5, s19
	v_rcp_f32_e32 v16, v33
	v_mov_b32_e32 v149, v81
	v_mul_f32_e32 v0, v1, v16
	v_mul_f32_e32 v1, v17, v16
	v_cvt_pk_bf16_f32 v0, v0, v1
	ds_write_b16 v168, v0
	ds_write_b16_d16_hi v169, v0
	v_rcp_f32_e32 v1, v34
	s_nop 0
	v_mul_f32_e32 v0, v2, v1
	v_mul_f32_e32 v1, v18, v1
	v_cvt_pk_bf16_f32 v0, v0, v1
	ds_write_b16 v170, v0
	ds_write_b16_d16_hi v171, v0
	v_or_b32_e32 v2, s12, v211
	v_rcp_f32_e32 v1, v35
	s_nop 0
	v_mul_f32_e32 v0, v3, v1
	v_mul_f32_e32 v1, v19, v1
	v_cvt_pk_bf16_f32 v0, v0, v1
	ds_write_b16 v172, v0
	ds_write_b16_d16_hi v173, v0
	v_rcp_f32_e32 v1, v36
	s_nop 0
	v_mul_f32_e32 v0, v4, v1
	v_mul_f32_e32 v1, v20, v1
	v_cvt_pk_bf16_f32 v0, v0, v1
	ds_write_b16 v174, v0
	ds_write_b16_d16_hi v175, v0
	v_or_b32_e32 v4, s12, v212
	v_rcp_f32_e32 v1, v37
	s_nop 0
	v_mul_f32_e32 v0, v5, v1
	v_mul_f32_e32 v1, v21, v1
	v_cvt_pk_bf16_f32 v0, v0, v1
	ds_write_b16 v176, v0
	ds_write_b16_d16_hi v177, v0
	v_rcp_f32_e32 v1, v38
	s_nop 0
	v_mul_f32_e32 v0, v6, v1
	v_mul_f32_e32 v1, v22, v1
	v_cvt_pk_bf16_f32 v1, v0, v1
	ds_write_b16 v178, v1
	ds_write_b16_d16_hi v179, v1
	v_or_b32_e32 v0, s12, v210
	v_or_b32_e32 v6, s12, v213
	v_readlane_b32 s12, v253, 37
	v_rcp_f32_e32 v3, v39
	s_cselect_b32 s12, s12, s18
	s_add_u32 s4, s12, s4
	s_addc_u32 s5, s5, s13
	v_mul_f32_e32 v1, v7, v3
	v_mul_f32_e32 v3, v23, v3
	v_cvt_pk_bf16_f32 v3, v1, v3
	ds_write_b16 v180, v3
	ds_write_b16_d16_hi v181, v3
	v_ashrrev_i32_e32 v7, 31, v6
	v_lshlrev_b64 v[6:7], s11, v[6:7]
	v_lshl_add_u64 v[6:7], v[150:151], 0, v[6:7]
	v_rcp_f32_e32 v5, v40
	v_ashrrev_i32_e32 v1, 31, v0
	v_lshlrev_b64 v[0:1], s11, v[0:1]
	v_lshl_add_u64 v[0:1], v[150:151], 0, v[0:1]
	v_mul_f32_e32 v3, v8, v5
	v_mul_f32_e32 v5, v24, v5
	v_cvt_pk_bf16_f32 v8, v3, v5
	ds_write_b16 v182, v8
	ds_write_b16_d16_hi v183, v8
	v_ashrrev_i32_e32 v3, 31, v2
	v_lshlrev_b64 v[2:3], s11, v[2:3]
	v_lshl_add_u64 v[2:3], v[150:151], 0, v[2:3]
	v_rcp_f32_e32 v16, v41
	v_ashrrev_i32_e32 v5, 31, v4
	v_lshlrev_b64 v[4:5], s11, v[4:5]
	v_lshl_add_u64 v[4:5], v[150:151], 0, v[4:5]
	v_mul_f32_e32 v8, v9, v16
	v_mul_f32_e32 v9, v25, v16
	v_cvt_pk_bf16_f32 v8, v8, v9
	ds_write_b16 v184, v8
	ds_write_b16_d16_hi v185, v8
	s_lshl_b64 s[12:13], s[16:17], 1
	s_and_b64 vcc, exec, s[46:47]
	s_mov_b32 s18, s1
	v_rcp_f32_e32 v9, v42
	s_nop 0
	v_mul_f32_e32 v8, v10, v9
	v_mul_f32_e32 v9, v26, v9
	v_cvt_pk_bf16_f32 v8, v8, v9
	ds_write_b16 v186, v8
	ds_write_b16_d16_hi v187, v8
	v_rcp_f32_e32 v9, v43
	s_nop 0
	v_mul_f32_e32 v8, v11, v9
	v_mul_f32_e32 v9, v27, v9
	v_cvt_pk_bf16_f32 v18, v8, v9
	v_mov_b64_e32 v[8:9], s[4:5]
	v_mad_u64_u32 v[10:11], s[4:5], v0, s40, v[8:9]
	ds_write_b16 v188, v18
	ds_write_b16_d16_hi v189, v18
	v_rcp_f32_e32 v0, v44
	v_mad_u64_u32 v[16:17], s[4:5], v2, s40, v[8:9]
	v_mad_u64_u32 v[18:19], s[4:5], v4, s40, v[8:9]
	v_mul_f32_e32 v2, v12, v0
	v_mul_f32_e32 v0, v28, v0
	v_cvt_pk_bf16_f32 v0, v2, v0
	v_mad_i32_i24 v11, v1, s40, v11
	ds_write_b16 v202, v0
	ds_write_b16_d16_hi v203, v0
	v_mad_i32_i24 v19, v5, s40, v19
	v_mad_u64_u32 v[8:9], s[4:5], v6, s40, v[8:9]
	v_rcp_f32_e32 v2, v45
	v_mad_i32_i24 v9, v7, s40, v9
	v_mad_i32_i24 v17, v3, s40, v17
	v_mul_f32_e32 v0, v13, v2
	v_mul_f32_e32 v1, v29, v2
	v_cvt_pk_bf16_f32 v4, v0, v1
	ds_write_b16 v204, v4
	ds_write_b16_d16_hi v205, v4
	v_lshl_add_u64 v[0:1], v[10:11], 0, s[12:13]
	v_rcp_f32_e32 v5, v46
	v_lshl_add_u64 v[2:3], v[16:17], 0, s[12:13]
	v_lshl_add_u64 v[16:17], v[8:9], 0, s[12:13]
	v_lshl_add_u64 v[20:21], v[2:3], 0, v[148:149]
	v_mul_f32_e32 v4, v14, v5
	v_mul_f32_e32 v5, v30, v5
	v_cvt_pk_bf16_f32 v6, v4, v5
	v_lshl_add_u64 v[4:5], v[18:19], 0, s[12:13]
	v_lshl_add_u64 v[18:19], v[0:1], 0, v[148:149]
	ds_write_b16 v206, v6
	ds_write_b16_d16_hi v207, v6
	v_lshl_add_u64 v[22:23], v[4:5], 0, v[148:149]
	v_rcp_f32_e32 v0, v47
	v_lshl_add_u64 v[16:17], v[16:17], 0, v[148:149]
	v_mul_f32_e32 v1, v15, v0
	v_mul_f32_e32 v0, v31, v0
	v_cvt_pk_bf16_f32 v0, v1, v0
	ds_write_b16 v208, v0
	ds_write_b16_d16_hi v209, v0
	s_waitcnt lgkmcnt(0)
	ds_read_b128 v[0:3], v229
	ds_read_b128 v[4:7], v230
	ds_read_b128 v[8:11], v231
	ds_read_b128 v[12:15], v232
	s_waitcnt lgkmcnt(3)
	global_store_dwordx4 v[18:19], v[0:3], off
	s_waitcnt lgkmcnt(2)
	global_store_dwordx4 v[20:21], v[4:7], off
	s_waitcnt lgkmcnt(1)
	global_store_dwordx4 v[22:23], v[8:11], off
	s_waitcnt lgkmcnt(0)
	global_store_dwordx4 v[16:17], v[12:15], off
	s_barrier
	s_cbranch_vccnz .LBB0_691

; __device__ __forceinline__ unsigned cvt_pk_bf16(float lo, float hi) { unsigned r; asm volatile("v_cvt_pk_bf16_f32 %0, %1, %2" : "=v"(r) : "v"(lo), "v"(hi)); return r; }
; __device__ __forceinline__ int crow(int r, int hi) { return (r & 3) + 8 * (r >> 2) + 4 * hi; }
; template <bool MERGE> __device__ __forceinline__ void compute_b(LAS unsigned char* lds, const UD& x, unsigned char* ws, unsigned char* dout, int wid, int lane, const u32x4 (&pw)[10], float mx, float lsum) {
;     ...
;     asm volatile("s_waitcnt lgkmcnt(0)" ::: "memory");
; #pragma unroll
;     for (int r = 0; r < 16; ++r) {
;         const int qrow = crow(r, hi); const float rl = __builtin_amdgcn_rcpf(wsf[qrow]);
;         const unsigned a = pg8::cvt_pk_bf16(o[0][r] * rl, o[1][r] * rl);
;         stg[qrow * 64 + r32] = (bf16_t)(a & 0xffffu); stg[qrow * 64 + 32 + r32] = (bf16_t)(a >> 16);
;     }
;     asm volatile("s_waitcnt lgkmcnt(0)" ::: "memory");
;     ...
;         const float* ST = (const float*)(ws + WS_STAT); bf16_t* MIX = (bf16_t*)(ws + WS_MIXN);
; #pragma unroll
;         for (int i0 = 0; i0 < 4; i0 += 2) {
;             u32x4 o1[2], o2[2]; float m1[2], l1[2], m2[2], l2[2];
; #pragma unroll
;             for (int ii = 0; ii < 2; ++ii) {
;                 const int row = (i0 + ii) * 8 + (lane >> 3), ch = lane & 7; const size_t tok = tokb + (size_t)(t0 + row);
;                 const float* s1 = ST + (((size_t)1 * M + tok) * NH + x.h) * 2; const float* s2 = ST + (((size_t)2 * M + tok) * NH + x.h) * 2;
;                 m1[ii] = s1[0]; l1[ii] = s1[1]; m2[ii] = s2[0]; l2[ii] = s2[1];
;                 o1[ii] = *(const u32x4*)(o_base(ws, dout, 1, x.b) + tok * AW + x.h * HD + ch * 8); o2[ii] = *(const u32x4*)(o_base(ws, dout, 2, x.b) + tok * AW + x.h * HD + ch * 8);
;             }
.LBB0_940:
	s_or_b64 exec, exec, s[18:19]
	s_waitcnt lgkmcnt(0)
	ds_read_b32 v32, v162
	ds_read_b32 v33, v162 offset:4
	ds_read_b32 v34, v162 offset:8
	ds_read_b32 v35, v162 offset:12
	ds_read_b32 v36, v162 offset:32
	ds_read_b32 v37, v162 offset:36
	ds_read_b32 v38, v162 offset:40
	ds_read_b32 v39, v162 offset:44
	ds_read_b32 v40, v162 offset:64
	ds_read_b32 v41, v162 offset:68
	ds_read_b32 v42, v162 offset:72
	ds_read_b32 v43, v162 offset:76
	ds_read_b32 v44, v162 offset:96
	ds_read_b32 v45, v162 offset:100
	ds_read_b32 v46, v162 offset:104
	ds_read_b32 v47, v162 offset:108
	s_waitcnt lgkmcnt(0)
	s_ashr_i32 s19, s22, 31
	s_mul_i32 s24, s0, 0x500000
	v_readlane_b32 s46, v254, 59
	s_mul_hi_i32 s23, s0, 0x500000
	v_rcp_f32_e32 v32, v32
	v_readlane_b32 s47, v254, 60
	v_mov_b32_e32 v145, v81
	v_mul_f32_e32 v0, v0, v32
	v_mul_f32_e32 v16, v16, v32
	v_cvt_pk_bf16_f32 v0, v0, v16
	ds_write_b16 v163, v0
	ds_write_b16_d16_hi v164, v0
	v_rcp_f32_e32 v0, v33
	s_nop 0
	v_mul_f32_e32 v1, v1, v0
	v_mul_f32_e32 v0, v17, v0
	v_cvt_pk_bf16_f32 v0, v1, v0
	ds_write_b16 v165, v0
	ds_write_b16_d16_hi v166, v0
	v_rcp_f32_e32 v0, v34
	s_nop 0
	v_mul_f32_e32 v1, v2, v0
	v_mul_f32_e32 v0, v18, v0
	v_cvt_pk_bf16_f32 v0, v1, v0
	ds_write_b16 v167, v0
	ds_write_b16_d16_hi v168, v0
	v_rcp_f32_e32 v0, v35
	s_nop 0
	v_mul_f32_e32 v1, v3, v0
	v_mul_f32_e32 v0, v19, v0
	v_cvt_pk_bf16_f32 v0, v1, v0
	ds_write_b16 v169, v0
	ds_write_b16_d16_hi v170, v0
	v_rcp_f32_e32 v0, v36
	s_nop 0
	v_mul_f32_e32 v1, v4, v0
	v_mul_f32_e32 v0, v20, v0
	v_cvt_pk_bf16_f32 v0, v1, v0
	ds_write_b16 v171, v0
	ds_write_b16_d16_hi v172, v0
	v_rcp_f32_e32 v0, v37
	s_nop 0
	v_mul_f32_e32 v1, v5, v0
	v_mul_f32_e32 v0, v21, v0
	v_cvt_pk_bf16_f32 v0, v1, v0
	ds_write_b16 v173, v0
	ds_write_b16_d16_hi v174, v0
	v_rcp_f32_e32 v0, v38
	s_nop 0
	v_mul_f32_e32 v1, v6, v0
	v_mul_f32_e32 v0, v22, v0
	v_cvt_pk_bf16_f32 v0, v1, v0
	ds_write_b16 v175, v0
	ds_write_b16_d16_hi v176, v0
	v_rcp_f32_e32 v0, v39
	s_nop 0
	v_mul_f32_e32 v1, v7, v0
	v_mul_f32_e32 v0, v23, v0
	v_cvt_pk_bf16_f32 v0, v1, v0
	ds_write_b16 v177, v0
	ds_write_b16_d16_hi v178, v0
	v_rcp_f32_e32 v0, v40
	s_nop 0
	v_mul_f32_e32 v1, v8, v0
	v_mul_f32_e32 v0, v24, v0
	v_cvt_pk_bf16_f32 v0, v1, v0
	ds_write_b16 v179, v0
	ds_write_b16_d16_hi v180, v0
	v_rcp_f32_e32 v0, v41
	s_nop 0
	v_mul_f32_e32 v1, v9, v0
	v_mul_f32_e32 v0, v25, v0
	v_cvt_pk_bf16_f32 v0, v1, v0
	ds_write_b16 v181, v0
	ds_write_b16_d16_hi v182, v0
	v_rcp_f32_e32 v0, v42
	s_nop 0
	v_mul_f32_e32 v1, v10, v0
	v_mul_f32_e32 v0, v26, v0
	v_cvt_pk_bf16_f32 v0, v1, v0
	ds_write_b16 v183, v0
	ds_write_b16_d16_hi v184, v0
	v_rcp_f32_e32 v0, v43
	s_nop 0
	v_mul_f32_e32 v1, v11, v0
	v_mul_f32_e32 v0, v27, v0
	v_cvt_pk_bf16_f32 v0, v1, v0
	ds_write_b16 v185, v0
	ds_write_b16_d16_hi v186, v0
	v_rcp_f32_e32 v0, v44
	s_nop 0
	v_mul_f32_e32 v1, v12, v0
	v_mul_f32_e32 v0, v28, v0
	v_cvt_pk_bf16_f32 v0, v1, v0
	ds_write_b16 v187, v0
	ds_write_b16_d16_hi v188, v0
	v_rcp_f32_e32 v0, v45
	s_nop 0
	v_mul_f32_e32 v1, v13, v0
	v_mul_f32_e32 v0, v29, v0
	v_cvt_pk_bf16_f32 v0, v1, v0
	ds_write_b16 v189, v0
	ds_write_b16_d16_hi v202, v0
	v_rcp_f32_e32 v0, v46
	s_nop 0
	v_mul_f32_e32 v1, v14, v0
	v_mul_f32_e32 v0, v30, v0
	v_cvt_pk_bf16_f32 v0, v1, v0
	ds_write_b16 v203, v0
	ds_write_b16_d16_hi v204, v0
	v_or_b32_e32 v14, s20, v207
	s_add_u32 s20, s22, 0x30000
	s_addc_u32 s21, s19, 0
	s_add_u32 s18, s22, 0x60000
	v_rcp_f32_e32 v0, v47
	s_addc_u32 s19, s19, 0
	s_lshl_b64 s[16:17], s[16:17], 1
	s_add_u32 s24, s46, s24
	s_addc_u32 s23, s47, s23
	v_mul_f32_e32 v1, v15, v0
	v_mul_f32_e32 v0, v31, v0
	s_add_u32 s24, s24, s16
	v_ashrrev_i32_e32 v15, 31, v14
	v_cvt_pk_bf16_f32 v0, v1, v0
	s_addc_u32 s25, s23, s17
	v_lshl_add_u64 v[24:25], s[14:15], 0, v[14:15]
	ds_write_b16 v205, v0
	ds_write_b16_d16_hi v206, v0
	v_lshl_add_u64 v[16:17], s[24:25], 0, v[144:145]
	v_mad_u64_u32 v[0:1], s[24:25], v24, 12, s[20:21]
	v_mad_i32_i24 v1, v25, 12, v1
	v_mad_u64_u32 v[2:3], s[24:25], v24, 12, s[18:19]
	s_waitcnt lgkmcnt(0)
	v_lshl_add_u64 v[0:1], v[0:1], 3, s[34:35]
	v_mad_i32_i24 v3, v25, 12, v3
	v_lshl_add_u64 v[2:3], v[2:3], 3, s[34:35]
	global_load_dwordx2 v[34:35], v[0:1], off
	global_load_dwordx2 v[36:37], v[2:3], off
	v_lshl_add_u64 v[12:13], v[136:137], 0, s[16:17]
	v_mad_u64_u32 v[0:1], s[24:25], v24, s40, v[12:13]
	v_mad_i32_i24 v1, v25, s40, v1
	global_load_dwordx4 v[8:11], v[0:1], off
	v_mad_u64_u32 v[0:1], s[24:25], v24, s40, v[16:17]
	v_mad_i32_i24 v1, v25, s40, v1
	global_load_dwordx4 v[26:29], v[0:1], off
	v_or_b32_e32 v0, 8, v14
	v_ashrrev_i32_e32 v1, 31, v0
	v_lshl_add_u64 v[18:19], s[14:15], 0, v[0:1]
	v_mad_u64_u32 v[0:1], s[24:25], v18, 12, s[20:21]
	v_mad_i32_i24 v1, v19, 12, v1
	v_mad_u64_u32 v[2:3], s[24:25], v18, 12, s[18:19]
	v_lshl_add_u64 v[0:1], v[0:1], 3, s[34:35]
	v_mad_i32_i24 v3, v19, 12, v3
	v_lshl_add_u64 v[2:3], v[2:3], 3, s[34:35]
	global_load_dwordx2 v[20:21], v[0:1], off
	global_load_dwordx2 v[22:23], v[2:3], off
	v_mad_u64_u32 v[0:1], s[24:25], v18, s40, v[12:13]
	v_mad_i32_i24 v1, v19, s40, v1
	global_load_dwordx4 v[0:3], v[0:1], off
	v_mad_u64_u32 v[4:5], s[24:25], v18, s40, v[16:17]
	v_mad_i32_i24 v5, v19, s40, v5
	global_load_dwordx4 v[4:7], v[4:5], off
	v_add_u32_e32 v15, v208, v209
	ds_read_b128 v[30:33], v15
	ds_read2_b32 v[38:39], v210 offset1:32
	v_lshlrev_b64 v[24:25], 11, v[24:25]
	v_lshl_add_u64 v[24:25], s[84:85], 0, v[24:25]
	v_lshl_add_u64 v[24:25], v[24:25], 0, s[16:17]
	v_lshl_add_u64 v[24:25], v[24:25], 0, v[144:145]
	s_cmp_gt_i32 s22, 3
	s_waitcnt vmcnt(6) lgkmcnt(0)
; __device__ __forceinline__ unsigned cvt_pk_bf16(float lo, float hi) { unsigned r; asm volatile("v_cvt_pk_bf16_f32 %0, %1, %2" : "=v"(r) : "v"(lo), "v"(hi)); return r; }
; #define LAS __attribute__((address_space(3)))
; template <bool MERGE> __device__ __forceinline__ void compute_b(LAS unsigned char* lds, const UD& x, unsigned char* ws, unsigned char* dout, int wid, int lane, const u32x4 (&pw)[10], float mx, float lsum) {
;     ...
; #pragma unroll
;             for (int ii = 0; ii < 2; ++ii) {
;                 const int row = (i0 + ii) * 8 + (lane >> 3), ch = lane & 7; const size_t tok = tokb + (size_t)(t0 + row);
;                 const u32x4 v0 = *(const LAS u32x4*)(stg + row * 64 + ch * 8);
;                 const float m0 = wsf[32 + row], l0 = wsf[row];
;                 const float mxx = fmaxf(fmaxf(m0, m1[ii]), m2[ii]);
;                 float w0 = __builtin_amdgcn_exp2f(m0 - mxx) * l0, w1 = __builtin_amdgcn_exp2f(m1[ii] - mxx) * l1[ii], w2 = __builtin_amdgcn_exp2f(m2[ii] - mxx) * l2[ii];
;                 const float rd = 1.0f / (w0 + w1 + w2); w0 *= rd; w1 *= rd; w2 *= rd;
;                 const u32x4 a1 = o1[ii], a2 = o2[ii];
;                 u32x4 w;
;                 w.x = pg8::cvt_pk_bf16(w0 * __uint_as_float(v0.x << 16) + w1 * __uint_as_float(a1.x << 16) + w2 * __uint_as_float(a2.x << 16), w0 * __uint_as_float(v0.x & 0xffff0000u) + w1 * __uint_as_float(a1.x & 0xffff0000u) + w2 * __uint_as_float(a2.x & 0xffff0000u));
;                 w.y = pg8::cvt_pk_bf16(w0 * __uint_as_float(v0.y << 16) + w1 * __uint_as_float(a1.y << 16) + w2 * __uint_as_float(a2.y << 16), w0 * __uint_as_float(v0.y & 0xffff0000u) + w1 * __uint_as_float(a1.y & 0xffff0000u) + w2 * __uint_as_float(a2.y & 0xffff0000u));
;                 w.z = pg8::cvt_pk_bf16(w0 * __uint_as_float(v0.z << 16) + w1 * __uint_as_float(a1.z << 16) + w2 * __uint_as_float(a2.z << 16), w0 * __uint_as_float(v0.z & 0xffff0000u) + w1 * __uint_as_float(a1.z & 0xffff0000u) + w2 * __uint_as_float(a2.z & 0xffff0000u));
;                 w.w = pg8::cvt_pk_bf16(w0 * __uint_as_float(v0.w << 16) + w1 * __uint_as_float(a1.w << 16) + w2 * __uint_as_float(a2.w << 16), w0 * __uint_as_float(v0.w & 0xffff0000u) + w1 * __uint_as_float(a1.w & 0xffff0000u) + w2 * __uint_as_float(a2.w & 0xffff0000u));
;                 *(u32x4*)(MIX + tok * DM + PWD + x.h * HD + ch * 8) = w;
;             }
	v_max3_f32 v15, v39, v34, v36
	v_sub_f32_e32 v39, v39, v15
	v_sub_f32_e32 v34, v34, v15
	v_sub_f32_e32 v15, v36, v15
	v_exp_f32_e32 v41, v39
	v_exp_f32_e32 v40, v15
	v_exp_f32_e32 v34, v34
	s_waitcnt vmcnt(5)
	v_lshlrev_b32_e32 v15, 16, v8
	v_and_b32_e32 v36, 0xffff0000, v8
	v_lshlrev_b32_e32 v42, 16, v9
	v_and_b32_e32 v43, 0xffff0000, v9
	v_mov_b32_e32 v8, v37
	v_mov_b32_e32 v9, v38
	v_pk_mul_f32 v[8:9], v[8:9], v[40:41]
	v_lshlrev_b32_e32 v44, 16, v10
	v_and_b32_e32 v45, 0xffff0000, v10
	v_fma_f32 v10, v35, v34, v9
	v_add_f32_e32 v10, v8, v10
	v_mul_f32_e32 v39, v35, v34
	v_div_scale_f32 v34, s[24:25], v10, v10, 1.0
	v_rcp_f32_e32 v35, v34
	v_lshlrev_b32_e32 v46, 16, v11
	v_fma_f32 v37, -v34, v35, 1.0
	v_fmac_f32_e32 v35, v37, v35
	v_div_scale_f32 v37, vcc, 1.0, v10, 1.0
	v_mul_f32_e32 v38, v37, v35
	v_fma_f32 v40, -v34, v38, v37
	v_fmac_f32_e32 v38, v40, v35
	v_fma_f32 v34, -v34, v38, v37
	v_div_fmas_f32 v34, v34, v35, v38
	v_div_fixup_f32 v10, v34, v10, 1.0
	v_pk_mul_f32 v[34:35], v[8:9], v[10:11] op_sel_hi:[1,0]
	s_waitcnt vmcnt(4)
	v_lshlrev_b32_e32 v8, 16, v26
	v_lshlrev_b32_e32 v9, 16, v30
	v_mul_f32_e32 v38, v39, v10
	v_pk_mul_f32 v[8:9], v[34:35], v[8:9]
	v_lshlrev_b32_e32 v37, 16, v31
	v_fma_f32 v9, v38, v15, v9
	v_add_f32_e32 v10, v8, v9
	v_and_b32_e32 v9, 0xffff0000, v30
	v_and_b32_e32 v8, 0xffff0000, v26
	v_pk_mul_f32 v[8:9], v[34:35], v[8:9]
	v_and_b32_e32 v31, 0xffff0000, v31
	v_fma_f32 v9, v38, v36, v9
	v_and_b32_e32 v30, 0xffff0000, v27
	v_add_f32_e32 v8, v8, v9
	v_lshlrev_b32_e32 v36, 16, v27
	v_pk_mul_f32 v[26:27], v[34:35], v[30:31]
	v_cvt_pk_bf16_f32 v8, v10, v8
	v_pk_mul_f32 v[36:37], v[34:35], v[36:37]
	v_fma_f32 v10, v38, v43, v27
	v_fma_f32 v9, v38, v42, v37
	v_add_f32_e32 v10, v26, v10
	v_lshlrev_b32_e32 v26, 16, v28
	v_lshlrev_b32_e32 v27, 16, v32
	v_add_f32_e32 v9, v36, v9
	v_pk_mul_f32 v[26:27], v[34:35], v[26:27]
	v_cvt_pk_bf16_f32 v9, v9, v10
	v_and_b32_e32 v11, 0xffff0000, v11
	v_fma_f32 v10, v38, v44, v27
	v_add_f32_e32 v10, v26, v10
	v_and_b32_e32 v27, 0xffff0000, v32
	v_and_b32_e32 v26, 0xffff0000, v28
	v_pk_mul_f32 v[26:27], v[34:35], v[26:27]
	s_waitcnt vmcnt(1)
	v_lshlrev_b32_e32 v28, 16, v1
	v_fma_f32 v15, v38, v45, v27
	v_add_f32_e32 v15, v26, v15
	v_lshlrev_b32_e32 v26, 16, v29
	v_lshlrev_b32_e32 v27, 16, v33
	v_pk_mul_f32 v[26:27], v[34:35], v[26:27]
	v_cvt_pk_bf16_f32 v10, v10, v15
	v_lshlrev_b32_e32 v30, 16, v2
	v_fma_f32 v15, v38, v46, v27
	v_add_f32_e32 v15, v26, v15
	v_and_b32_e32 v27, 0xffff0000, v33
	v_and_b32_e32 v26, 0xffff0000, v29
	v_pk_mul_f32 v[26:27], v[34:35], v[26:27]
	v_and_b32_e32 v29, 0xffff0000, v1
	v_fma_f32 v11, v38, v11, v27
	v_add_f32_e32 v11, v26, v11
	v_cvt_pk_bf16_f32 v11, v15, v11
	global_store_dwordx4 v[24:25], v[8:11], off offset:512
	ds_read_b128 v[8:11], v229
	ds_read2_b32 v[26:27], v210 offset0:8 offset1:40
	v_and_b32_e32 v31, 0xffff0000, v2
	v_lshlrev_b32_e32 v32, 16, v3
	s_waitcnt lgkmcnt(0)
	v_max3_f32 v15, v27, v20, v22
	v_sub_f32_e32 v24, v27, v15
	v_sub_f32_e32 v20, v20, v15
	v_sub_f32_e32 v15, v22, v15
	v_exp_f32_e32 v25, v24
	v_exp_f32_e32 v24, v15
	v_exp_f32_e32 v20, v20
	v_lshlrev_b32_e32 v15, 16, v0
	v_and_b32_e32 v22, 0xffff0000, v0
	v_mov_b32_e32 v0, v23
	v_mov_b32_e32 v1, v26
	v_pk_mul_f32 v[0:1], v[0:1], v[24:25]
	v_mul_f32_e32 v27, v21, v20
	v_fma_f32 v2, v21, v20, v1
	v_add_f32_e32 v2, v0, v2
	v_div_scale_f32 v20, s[24:25], v2, v2, 1.0
	v_rcp_f32_e32 v21, v20
	s_nop 0
	v_fma_f32 v23, -v20, v21, 1.0
	v_fmac_f32_e32 v21, v23, v21
	v_div_scale_f32 v23, vcc, 1.0, v2, 1.0
	v_mul_f32_e32 v24, v23, v21
	v_fma_f32 v25, -v20, v24, v23
	v_fmac_f32_e32 v24, v25, v21
	v_fma_f32 v20, -v20, v24, v23
	v_div_fmas_f32 v20, v20, v21, v24
	v_div_fixup_f32 v2, v20, v2, 1.0
	v_pk_mul_f32 v[20:21], v[0:1], v[2:3] op_sel_hi:[1,0]
	s_waitcnt vmcnt(1)
	v_lshlrev_b32_e32 v0, 16, v4
	v_lshlrev_b32_e32 v1, 16, v8
	v_mul_f32_e32 v24, v27, v2
	v_pk_mul_f32 v[0:1], v[20:21], v[0:1]
	v_lshlrev_b32_e32 v23, 16, v9
	v_fma_f32 v1, v24, v15, v1
	v_add_f32_e32 v2, v0, v1
	v_and_b32_e32 v1, 0xffff0000, v8
	v_and_b32_e32 v0, 0xffff0000, v4
	v_pk_mul_f32 v[0:1], v[20:21], v[0:1]
	v_and_b32_e32 v9, 0xffff0000, v9
	v_fma_f32 v1, v24, v22, v1
	v_and_b32_e32 v8, 0xffff0000, v5
	v_add_f32_e32 v0, v0, v1
	v_lshlrev_b32_e32 v22, 16, v5
	v_pk_mul_f32 v[4:5], v[20:21], v[8:9]
	v_cvt_pk_bf16_f32 v0, v2, v0
	v_pk_mul_f32 v[22:23], v[20:21], v[22:23]
	v_fma_f32 v2, v24, v29, v5
	v_fma_f32 v1, v24, v28, v23
	v_add_f32_e32 v2, v4, v2
	v_lshlrev_b32_e32 v4, 16, v6
	v_lshlrev_b32_e32 v5, 16, v10
	v_add_f32_e32 v1, v22, v1
	v_pk_mul_f32 v[4:5], v[20:21], v[4:5]
	v_cvt_pk_bf16_f32 v1, v1, v2
	v_and_b32_e32 v3, 0xffff0000, v3
	v_fma_f32 v2, v24, v30, v5
	v_add_f32_e32 v2, v4, v2
	v_and_b32_e32 v5, 0xffff0000, v10
	v_and_b32_e32 v4, 0xffff0000, v6
	v_pk_mul_f32 v[4:5], v[20:21], v[4:5]
	s_nop 0
	v_fma_f32 v5, v24, v31, v5
	v_add_f32_e32 v4, v4, v5
	v_cvt_pk_bf16_f32 v2, v2, v4
	v_lshlrev_b32_e32 v4, 16, v7
	v_lshlrev_b32_e32 v5, 16, v11
	v_pk_mul_f32 v[4:5], v[20:21], v[4:5]
	s_nop 0
	v_fma_f32 v5, v24, v32, v5
	v_add_f32_e32 v6, v4, v5
	v_and_b32_e32 v5, 0xffff0000, v11
	v_and_b32_e32 v4, 0xffff0000, v7
	v_pk_mul_f32 v[4:5], v[20:21], v[4:5]
	s_nop 0
	v_fma_f32 v3, v24, v3, v5
	v_add_f32_e32 v3, v4, v3
	v_lshlrev_b64 v[4:5], 11, v[18:19]
	v_lshl_add_u64 v[4:5], s[84:85], 0, v[4:5]
	v_lshl_add_u64 v[4:5], v[4:5], 0, s[16:17]
	v_lshl_add_u64 v[4:5], v[4:5], 0, v[144:145]
	v_cvt_pk_bf16_f32 v3, v6, v3
	global_store_dwordx4 v[4:5], v[0:3], off offset:512
	s_nop 1
	v_or_b32_e32 v0, 16, v14
	v_ashrrev_i32_e32 v1, 31, v0
	v_lshl_add_u64 v[30:31], s[14:15], 0, v[0:1]
	v_mad_u64_u32 v[0:1], s[24:25], v30, 12, s[20:21]
	v_mad_i32_i24 v1, v31, 12, v1
	v_mad_u64_u32 v[2:3], s[24:25], v30, 12, s[18:19]
	v_lshl_add_u64 v[0:1], v[0:1], 3, s[34:35]
	v_mad_i32_i24 v3, v31, 12, v3
	v_lshl_add_u64 v[2:3], v[2:3], 3, s[34:35]
	global_load_dwordx2 v[32:33], v[0:1], off
	global_load_dwordx2 v[34:35], v[2:3], off
	v_mad_u64_u32 v[0:1], s[24:25], v30, s40, v[12:13]
	v_mad_i32_i24 v1, v31, s40, v1
	global_load_dwordx4 v[18:21], v[0:1], off
	v_mad_u64_u32 v[0:1], s[24:25], v30, s40, v[16:17]
	v_mad_i32_i24 v1, v31, s40, v1
	global_load_dwordx4 v[22:25], v[0:1], off
	v_or_b32_e32 v0, 24, v14
	v_ashrrev_i32_e32 v1, 31, v0
	v_lshl_add_u64 v[8:9], s[14:15], 0, v[0:1]
	v_mad_u64_u32 v[0:1], s[14:15], v8, 12, s[20:21]
	v_mad_i32_i24 v1, v9, 12, v1
	v_mad_u64_u32 v[2:3], s[14:15], v8, 12, s[18:19]
	v_lshl_add_u64 v[0:1], v[0:1], 3, s[34:35]
	v_mad_i32_i24 v3, v9, 12, v3
	v_lshl_add_u64 v[2:3], v[2:3], 3, s[34:35]
	global_load_dwordx2 v[10:11], v[0:1], off
	global_load_dwordx2 v[14:15], v[2:3], off
	v_mad_u64_u32 v[0:1], s[14:15], v8, s40, v[12:13]
	v_mad_i32_i24 v1, v9, s40, v1
	global_load_dwordx4 v[0:3], v[0:1], off
	v_mad_u64_u32 v[4:5], s[14:15], v8, s40, v[16:17]
	v_mad_i32_i24 v5, v9, s40, v5
	global_load_dwordx4 v[4:7], v[4:5], off
	ds_read_b128 v[26:29], v230
	ds_read2_b32 v[12:13], v210 offset0:16 offset1:48
	s_waitcnt vmcnt(6) lgkmcnt(0)
; #define LAS __attribute__((address_space(3)))
; template <bool MERGE> __device__ __forceinline__ void compute_b(LAS unsigned char* lds, const UD& x, unsigned char* ws, unsigned char* dout, int wid, int lane, const u32x4 (&pw)[10], float mx, float lsum) {
;     ...
; #pragma unroll
;         for (int i0 = 0; i0 < 4; i0 += 2) {
;             u32x4 o1[2], o2[2]; float m1[2], l1[2], m2[2], l2[2];
; #pragma unroll
;             for (int ii = 0; ii < 2; ++ii) {
;                 const int row = (i0 + ii) * 8 + (lane >> 3), ch = lane & 7; const size_t tok = tokb + (size_t)(t0 + row);
;                 const float* s1 = ST + (((size_t)1 * M + tok) * NH + x.h) * 2; const float* s2 = ST + (((size_t)2 * M + tok) * NH + x.h) * 2;
;                 m1[ii] = s1[0]; l1[ii] = s1[1]; m2[ii] = s2[0]; l2[ii] = s2[1];
;                 o1[ii] = *(const u32x4*)(o_base(ws, dout, 1, x.b) + tok * AW + x.h * HD + ch * 8); o2[ii] = *(const u32x4*)(o_base(ws, dout, 2, x.b) + tok * AW + x.h * HD + ch * 8);
;             }
; #pragma unroll
;             for (int ii = 0; ii < 2; ++ii) {
;                 const int row = (i0 + ii) * 8 + (lane >> 3), ch = lane & 7; const size_t tok = tokb + (size_t)(t0 + row);
;                 const u32x4 v0 = *(const LAS u32x4*)(stg + row * 64 + ch * 8);
;                 const float m0 = wsf[32 + row], l0 = wsf[row];
;                 const float mxx = fmaxf(fmaxf(m0, m1[ii]), m2[ii]);
;                 float w0 = __builtin_amdgcn_exp2f(m0 - mxx) * l0, w1 = __builtin_amdgcn_exp2f(m1[ii] - mxx) * l1[ii], w2 = __builtin_amdgcn_exp2f(m2[ii] - mxx) * l2[ii];
;                 const float rd = 1.0f / (w0 + w1 + w2); w0 *= rd; w1 *= rd; w2 *= rd;
;                 const u32x4 a1 = o1[ii], a2 = o2[ii];
;                 u32x4 w;
;                 w.x = pg8::cvt_pk_bf16(w0 * __uint_as_float(v0.x << 16) + w1 * __uint_as_float(a1.x << 16) + w2 * __uint_as_float(a2.x << 16), w0 * __uint_as_float(v0.x & 0xffff0000u) + w1 * __uint_as_float(a1.x & 0xffff0000u) + w2 * __uint_as_float(a2.x & 0xffff0000u));
;                 w.y = pg8::cvt_pk_bf16(w0 * __uint_as_float(v0.y << 16) + w1 * __uint_as_float(a1.y << 16) + w2 * __uint_as_float(a2.y << 16), w0 * __uint_as_float(v0.y & 0xffff0000u) + w1 * __uint_as_float(a1.y & 0xffff0000u) + w2 * __uint_as_float(a2.y & 0xffff0000u));
	v_max3_f32 v16, v13, v32, v34
	v_sub_f32_e32 v13, v13, v16
	v_exp_f32_e32 v17, v13
	v_sub_f32_e32 v13, v32, v16
	v_exp_f32_e32 v32, v13
	v_sub_f32_e32 v13, v34, v16
	v_exp_f32_e32 v16, v13
	s_waitcnt vmcnt(5)
	v_lshlrev_b32_e32 v34, 16, v18
	v_and_b32_e32 v37, 0xffff0000, v18
	v_lshlrev_b32_e32 v38, 16, v19
	v_and_b32_e32 v39, 0xffff0000, v19
	v_mov_b32_e32 v18, v35
	v_mov_b32_e32 v19, v12
	v_pk_mul_f32 v[12:13], v[18:19], v[16:17]
	v_mul_f32_e32 v36, v33, v32
	v_fma_f32 v16, v33, v32, v13
	v_add_f32_e32 v16, v12, v16
	v_div_scale_f32 v17, s[14:15], v16, v16, 1.0
	v_rcp_f32_e32 v18, v17
	v_lshlrev_b32_e32 v40, 16, v20
	v_and_b32_e32 v20, 0xffff0000, v20
	v_lshlrev_b32_e32 v41, 16, v21
	v_fma_f32 v19, -v17, v18, 1.0
	v_fmac_f32_e32 v18, v19, v18
	v_div_scale_f32 v19, vcc, 1.0, v16, 1.0
	v_mul_f32_e32 v32, v19, v18
	v_fma_f32 v33, -v17, v32, v19
	v_fmac_f32_e32 v32, v33, v18
	v_fma_f32 v17, -v17, v32, v19
	v_div_fmas_f32 v17, v17, v18, v32
	v_div_fixup_f32 v16, v17, v16, 1.0
	v_mul_f32_e32 v32, v36, v16
	v_pk_mul_f32 v[12:13], v[12:13], v[16:17] op_sel_hi:[1,0]
	s_waitcnt vmcnt(4)
	v_lshlrev_b32_e32 v16, 16, v22
	v_lshlrev_b32_e32 v17, 16, v26
	v_pk_mul_f32 v[16:17], v[12:13], v[16:17]
	v_lshlrev_b32_e32 v19, 16, v27
	v_fma_f32 v17, v32, v34, v17
	v_add_f32_e32 v18, v16, v17
	v_and_b32_e32 v17, 0xffff0000, v26
	v_and_b32_e32 v16, 0xffff0000, v22
	v_pk_mul_f32 v[16:17], v[12:13], v[16:17]
	s_waitcnt vmcnt(1)
	v_and_b32_e32 v26, 0xffff0000, v2
	v_fma_f32 v17, v32, v37, v17
	v_add_f32_e32 v16, v16, v17
	v_cvt_pk_bf16_f32 v16, v18, v16
	v_lshlrev_b32_e32 v18, 16, v23
	v_pk_mul_f32 v[18:19], v[12:13], v[18:19]
	s_nop 0
	v_fma_f32 v17, v32, v38, v19
	v_add_f32_e32 v17, v18, v17
	v_and_b32_e32 v19, 0xffff0000, v27
	v_and_b32_e32 v18, 0xffff0000, v23
	v_pk_mul_f32 v[18:19], v[12:13], v[18:19]
	v_lshlrev_b32_e32 v23, 16, v29
	v_fma_f32 v19, v32, v39, v19
	v_add_f32_e32 v18, v18, v19
	v_cvt_pk_bf16_f32 v17, v17, v18
	v_lshlrev_b32_e32 v18, 16, v24
	v_lshlrev_b32_e32 v19, 16, v28
	v_pk_mul_f32 v[18:19], v[12:13], v[18:19]
	v_lshlrev_b32_e32 v27, 16, v3
	v_fma_f32 v19, v32, v40, v19
	v_add_f32_e32 v22, v18, v19
	v_and_b32_e32 v19, 0xffff0000, v28
	v_and_b32_e32 v18, 0xffff0000, v24
	v_pk_mul_f32 v[18:19], v[12:13], v[18:19]
	v_and_b32_e32 v24, 0xffff0000, v1
	v_fma_f32 v19, v32, v20, v19
	v_add_f32_e32 v18, v18, v19
	v_cvt_pk_bf16_f32 v18, v22, v18
	v_lshlrev_b32_e32 v22, 16, v25
	v_pk_mul_f32 v[22:23], v[12:13], v[22:23]
	v_and_b32_e32 v20, 0xffff0000, v25
	v_fma_f32 v19, v32, v41, v23
	v_add_f32_e32 v19, v22, v19
	v_and_b32_e32 v22, 0xffff0000, v21
	v_and_b32_e32 v21, 0xffff0000, v29
	v_pk_mul_f32 v[12:13], v[12:13], v[20:21]
	v_lshlrev_b32_e32 v23, 16, v1
	v_fma_f32 v13, v32, v22, v13
	v_add_f32_e32 v12, v12, v13
	v_cvt_pk_bf16_f32 v19, v19, v12
	v_lshlrev_b64 v[12:13], 11, v[30:31]
	v_lshl_add_u64 v[12:13], s[84:85], 0, v[12:13]
	v_lshl_add_u64 v[12:13], v[12:13], 0, s[16:17]
	v_lshl_add_u64 v[12:13], v[12:13], 0, v[144:145]
	global_store_dwordx4 v[12:13], v[16:19], off offset:512
	ds_read_b128 v[16:19], v231
	ds_read2_b32 v[12:13], v210 offset0:24 offset1:56
	v_and_b32_e32 v22, 0xffff0000, v0
	v_lshlrev_b32_e32 v25, 16, v2
	s_waitcnt lgkmcnt(0)
	v_max3_f32 v20, v13, v10, v14
	v_sub_f32_e32 v13, v13, v20
	v_sub_f32_e32 v14, v14, v20
	v_exp_f32_e32 v21, v13
	v_sub_f32_e32 v10, v10, v20
	v_exp_f32_e32 v20, v14
	v_exp_f32_e32 v10, v10
	v_lshlrev_b32_e32 v14, 16, v0
	v_mov_b32_e32 v0, v15
	v_mov_b32_e32 v1, v12
	v_pk_mul_f32 v[0:1], v[0:1], v[20:21]
	v_mul_f32_e32 v13, v11, v10
	v_fma_f32 v2, v11, v10, v1
	v_add_f32_e32 v2, v0, v2
	v_div_scale_f32 v10, s[14:15], v2, v2, 1.0
	v_rcp_f32_e32 v11, v10
	s_nop 0
	v_fma_f32 v12, -v10, v11, 1.0
	v_fmac_f32_e32 v11, v12, v11
	v_div_scale_f32 v12, vcc, 1.0, v2, 1.0
	v_mul_f32_e32 v15, v12, v11
	v_fma_f32 v20, -v10, v15, v12
	v_fmac_f32_e32 v15, v20, v11
	v_fma_f32 v10, -v10, v15, v12
	v_div_fmas_f32 v10, v10, v11, v15
	v_div_fixup_f32 v2, v10, v2, 1.0
	v_pk_mul_f32 v[10:11], v[0:1], v[2:3] op_sel_hi:[1,0]
	s_waitcnt vmcnt(1)
	v_lshlrev_b32_e32 v0, 16, v4
	v_lshlrev_b32_e32 v1, 16, v16
	v_mul_f32_e32 v15, v13, v2
	v_pk_mul_f32 v[0:1], v[10:11], v[0:1]
	v_lshlrev_b32_e32 v12, 16, v5
	v_fma_f32 v1, v15, v14, v1
	v_add_f32_e32 v2, v0, v1
	v_and_b32_e32 v1, 0xffff0000, v16
	v_and_b32_e32 v0, 0xffff0000, v4
	v_pk_mul_f32 v[0:1], v[10:11], v[0:1]
	v_lshlrev_b32_e32 v13, 16, v17
	v_fma_f32 v1, v15, v22, v1
	v_pk_mul_f32 v[12:13], v[10:11], v[12:13]
	v_add_f32_e32 v0, v0, v1
	v_fma_f32 v1, v15, v23, v13
	v_add_f32_e32 v1, v12, v1
	v_and_b32_e32 v13, 0xffff0000, v17
	v_and_b32_e32 v12, 0xffff0000, v5
	v_pk_mul_f32 v[4:5], v[10:11], v[12:13]
	v_cvt_pk_bf16_f32 v0, v2, v0
	v_and_b32_e32 v3, 0xffff0000, v3
	v_fma_f32 v2, v15, v24, v5
	v_add_f32_e32 v2, v4, v2
	v_lshlrev_b32_e32 v4, 16, v6
	v_lshlrev_b32_e32 v5, 16, v18
	v_pk_mul_f32 v[4:5], v[10:11], v[4:5]
	v_cvt_pk_bf16_f32 v1, v1, v2
	s_nop 0
	v_fma_f32 v2, v15, v25, v5
	v_add_f32_e32 v2, v4, v2
	v_and_b32_e32 v5, 0xffff0000, v18
	v_and_b32_e32 v4, 0xffff0000, v6
	v_pk_mul_f32 v[4:5], v[10:11], v[4:5]
	s_nop 0
	v_fma_f32 v5, v15, v26, v5
	v_add_f32_e32 v4, v4, v5
	v_cvt_pk_bf16_f32 v2, v2, v4
	v_lshlrev_b32_e32 v4, 16, v7
	v_lshlrev_b32_e32 v5, 16, v19
	v_pk_mul_f32 v[4:5], v[10:11], v[4:5]
	s_nop 0
	v_fma_f32 v5, v15, v27, v5
	v_add_f32_e32 v6, v4, v5
	v_and_b32_e32 v5, 0xffff0000, v19
	v_and_b32_e32 v4, 0xffff0000, v7
	v_pk_mul_f32 v[4:5], v[10:11], v[4:5]
	s_nop 0
	v_fma_f32 v3, v15, v3, v5
	v_add_f32_e32 v3, v4, v3
	v_lshlrev_b64 v[4:5], 11, v[8:9]
	v_lshl_add_u64 v[4:5], s[84:85], 0, v[4:5]
	v_lshl_add_u64 v[4:5], v[4:5], 0, s[16:17]
	v_lshl_add_u64 v[4:5], v[4:5], 0, v[144:145]
	v_cvt_pk_bf16_f32 v3, v6, v3
	global_store_dwordx4 v[4:5], v[0:3], off offset:512
	s_cbranch_scc1 .LBB0_902
; template <bool MERGE> __device__ __forceinline__ void compute_b(LAS unsigned char* lds, const UD& x, unsigned char* ws, unsigned char* dout, int wid, int lane, const u32x4 (&pw)[10], float mx, float lsum) {
;     ...
;         if (x.h < 4) {
;             const int g = x.h, hw = 1 << g;
;             const bf16_t* VP = (const bf16_t*)(ws + off_vp(x.b));
; #pragma unroll 1
;             for (int p = 0; p < 8; ++p) {
;                 const int s = t0 + 4 * p + (lane >> 4);
;                 const bf16_t* base = VP + tokb * PWD + g * 64 + 4 * (lane & 15);
;                 float s0 = 0.f, s1 = 0.f, s2 = 0.f, s3 = 0.f; int cnt = 0;
;                 const u32x2 me = *(const u32x2*)(base + (size_t)s * PWD);
	s_bfe_u32 s14, s45, 0x30008
	s_lshl_b32 s18, s14, 17
	s_lshl_b32 s19, s14, 8
	s_lshl_b32 s20, -1, s22
	s_mul_i32 s15, s0, 0xa00000
	v_readlane_b32 s24, v252, 1
	s_mul_hi_i32 s14, s0, 0xa00000
	v_readlane_b32 s25, v252, 2
	s_add_u32 s21, s24, s15
	s_addc_u32 s23, s25, s14
	s_lshl_b64 s[14:15], s[0:1], 20
	s_add_u32 s14, s21, s14
	s_addc_u32 s15, s23, s15
	s_add_u32 s14, s14, s16
	s_addc_u32 s15, s15, s17
	v_add_u32_e32 v0, s19, v212
	s_cmp_lg_u32 s22, 0
	v_ashrrev_i32_e32 v1, 31, v0
	v_mov_b32_e32 v147, v81
	s_cselect_b64 s[46:47], -1, 0
	s_cmp_gt_u32 s22, 1
	v_lshlrev_b64 v[4:5], 11, v[0:1]
	v_lshlrev_b64 v[6:7], 9, v[0:1]
	v_lshl_add_u64 v[0:1], s[14:15], 0, v[146:147]
	s_mov_b64 s[14:15], 0xc400000
	s_cselect_b64 s[54:55], -1, 0
	s_cmp_gt_u32 s22, 2
	v_lshl_add_u64 v[0:1], v[0:1], 0, s[14:15]
	s_cselect_b64 s[56:57], -1, 0
	s_lshl_b32 s14, s20, 9
	s_add_i32 s14, s14, s18
	v_add_u32_e32 v2, s14, v211
	s_add_i32 s19, s19, s20
	s_lshl_b64 s[14:15], s[0:1], 22
	s_add_u32 s14, s16, s14
	s_addc_u32 s15, s17, s15
	s_mul_hi_i32 s1, s0, 0xb00000
	s_mul_i32 s0, s0, 0xb00000
	s_add_u32 s0, s16, s0
	s_addc_u32 s1, s17, s1
	v_lshl_add_u64 v[4:5], s[14:15], 0, v[4:5]
	v_lshl_add_u64 v[6:7], s[0:1], 0, v[6:7]
	v_add_u32_e32 v3, s19, v213
	v_lshl_add_u64 v[4:5], v[138:139], 0, v[4:5]
	v_lshl_add_u64 v[6:7], v[140:141], 0, v[6:7]
	s_mov_b64 s[58:59], 0
	s_branch .LBB0_944

; #define PG8_STAGE(bufoff, gbase, voff) do { _Pragma("unroll") for (int _i = 0; _i < 2; ++_i) \
;         __builtin_amdgcn_global_load_lds((const unsigned*)((const char*)(gbase) + (voff)[_i]), (PG8_LAS unsigned*)(lds + (bufoff) + ldsw + _i * 8192), 16, 0, 0); } while (0)
; #define PG8_LDA(dst, b, h) do { _Pragma("unroll") for (int m = 0; m < 4; ++m) _Pragma("unroll") for (int k = 0; k < 2; ++k) dst[m][k] = *(const PG8_LAS bf16x8*)(lds + PG8_SA(b, h) + aoff + m * 2048 + k * 1024); } while (0)
; #define PG8_LDB(dst, b, h) do { _Pragma("unroll") for (int n = 0; n < 2; ++n) _Pragma("unroll") for (int k = 0; k < 2; ++k) dst[n][k] = *(const PG8_LAS bf16x8*)(lds + PG8_SB(b, h) + boff + n * 2048 + k * 1024); } while (0)
; #define PG8_MMA(ai, bj, At, Bt) do { __builtin_amdgcn_s_setprio(1); _Pragma("unroll") for (int m = 0; m < 4; ++m) _Pragma("unroll") for (int n = 0; n < 2; ++n) _Pragma("unroll") for (int k = 0; k < 2; ++k) \
;         acc[ai][bj][m][n] = __builtin_amdgcn_mfma_f32_16x16x32_bf16(Bt[n][k], At[m][k], acc[ai][bj][m][n], 0, 0, 0); __builtin_amdgcn_s_setprio(0); } while (0)
; #define PG8_WAIT_V(n) asm volatile("s_waitcnt vmcnt(" #n ")" ::: "memory")
; #define PG8_BAR __builtin_amdgcn_s_barrier()
; template <class Epi, class Sched, bool ALIGN_EPI = false, bool SP2 = false, bool HALFM = false>
; __device__ __forceinline__ void gemm_phase(PG8_LAS unsigned char* lds, const Gemm g, const Sched& S, const Epi& E) {
;     ...
;             const bool last = (t == nt - 2);
;             const char* a1 = cA + (size_t)(t + 1) * kstep;
;             const char* a2 = last ? nA : cA + (size_t)(t + 2) * kstep; const char* b2 = last ? nB : cB + (size_t)(t + 2) * kstep;
;             const char* a3 = a2 + kstep; const char* b3 = b2 + kstep;
;             if (last && has_next) S.a_ready(nxt);
;             if constexpr (SP2) {
;             PG8_LDB(B0, 0, 0); PG8_LDB(B1, 0, 1); PG8_SCHED; PG8_LDA(At, 0, 0); PG8_STAGE(PG8_SA(1, 1), a1 + hstep, voffA);
;             PG8_WAIT_V(8); PG8_WAIT_L(0); PG8_BAR; PG8_MMA(0, 0, At, B0); PG8_MMA(0, 1, At, B1); PG8_BAR; PG8_SCHED;
;             if constexpr (!HALFM) PG8_LDA(At, 0, 1); PG8_STAGE(PG8_SB(0, 0), b2, voffB); PG8_STAGE(PG8_SB(0, 1), b2 + hstep, voffB); PG8_STAGE(PG8_SA(0, 0), a2, voffA);
;             PG8_WAIT_V(8); PG8_WAIT_L(0); PG8_BAR; if constexpr (!HALFM) { PG8_MMA(1, 0, At, B0); PG8_MMA(1, 1, At, B1); } PG8_BAR; PG8_SCHED;
.LBB0_1165:
	s_add_u32 s20, s18, 0xfffc0080
	s_addc_u32 s21, s19, -1
	s_add_i32 s57, 0, 0x10000
	s_cmp_eq_u32 s56, 12
	s_cselect_b32 s23, s13, s21
	s_cselect_b32 s22, s52, s20
	s_cselect_b32 s21, s11, s55
	s_cselect_b32 s20, s53, s54
	s_add_i32 s60, 0, 0x14000
	v_add_u32_e32 v142, s57, v189
	v_add_u32_e32 v174, s60, v189
	ds_read_b128 v[130:133], v142
	ds_read_b128 v[134:137], v142 offset:1024
	ds_read_b128 v[138:141], v142 offset:2048
	ds_read_b128 v[142:145], v142 offset:3072
	ds_read_b128 v[146:149], v174
	ds_read_b128 v[150:153], v174 offset:1024
	ds_read_b128 v[170:173], v174 offset:2048
	ds_read_b128 v[174:177], v174 offset:3072
	v_lshl_add_u64 v[186:187], s[18:19], 0, v[166:167]
	s_add_i32 m0, s27, 0xc000
	ds_read_b128 v[178:181], v203
	ds_read_b128 v[182:185], v203 offset:1024
	ds_read_b128 v[196:199], v203 offset:2048
	ds_read_b128 v[204:207], v203 offset:3072
	ds_read_b128 v[208:211], v203 offset:4096
	ds_read_b128 v[212:215], v203 offset:5120
	ds_read_b128 v[216:219], v203 offset:6144
	ds_read_b128 v[220:223], v203 offset:7168
	global_load_lds_dwordx4 v[186:187], off
	v_lshl_add_u64 v[186:187], s[18:19], 0, v[168:169]
	s_add_i32 m0, s27, 0xe000
	s_nop 0
	global_load_lds_dwordx4 v[186:187], off
	s_waitcnt vmcnt(8)
	s_waitcnt lgkmcnt(0)
	s_setprio 1
	s_barrier
	v_mfma_f32_16x16x32_bf16 v[126:129], v[130:133], v[178:181], v[126:129]
	v_mfma_f32_16x16x32_bf16 v[122:125], v[138:141], v[178:181], v[122:125]
	v_mfma_f32_16x16x32_bf16 v[110:113], v[130:133], v[196:199], v[110:113]
	v_mfma_f32_16x16x32_bf16 v[106:109], v[138:141], v[196:199], v[106:109]
	v_mfma_f32_16x16x32_bf16 v[94:97], v[130:133], v[208:211], v[94:97]
	v_mfma_f32_16x16x32_bf16 v[90:93], v[138:141], v[208:211], v[90:93]
	v_mfma_f32_16x16x32_bf16 v[76:79], v[130:133], v[216:219], v[76:79]
	v_mfma_f32_16x16x32_bf16 v[72:75], v[138:141], v[216:219], v[72:75]
	v_mfma_f32_16x16x32_bf16 v[126:129], v[134:137], v[182:185], v[126:129]
	v_mfma_f32_16x16x32_bf16 v[122:125], v[142:145], v[182:185], v[122:125]
	v_mfma_f32_16x16x32_bf16 v[110:113], v[134:137], v[204:207], v[110:113]
	v_mfma_f32_16x16x32_bf16 v[106:109], v[142:145], v[204:207], v[106:109]
	v_mfma_f32_16x16x32_bf16 v[94:97], v[134:137], v[212:215], v[94:97]
	v_mfma_f32_16x16x32_bf16 v[90:93], v[142:145], v[212:215], v[90:93]
	v_mfma_f32_16x16x32_bf16 v[76:79], v[134:137], v[220:223], v[76:79]
	v_mfma_f32_16x16x32_bf16 v[72:75], v[142:145], v[220:223], v[72:75]
	v_mfma_f32_16x16x32_bf16 v[118:121], v[146:149], v[178:181], v[118:121]
	v_mfma_f32_16x16x32_bf16 v[114:117], v[170:173], v[178:181], v[114:117]
	v_mfma_f32_16x16x32_bf16 v[102:105], v[146:149], v[196:199], v[102:105]
	v_mfma_f32_16x16x32_bf16 v[98:101], v[170:173], v[196:199], v[98:101]
	v_mfma_f32_16x16x32_bf16 v[86:89], v[146:149], v[208:211], v[86:89]
	v_mfma_f32_16x16x32_bf16 v[82:85], v[170:173], v[208:211], v[82:85]
	v_mfma_f32_16x16x32_bf16 v[68:71], v[146:149], v[216:219], v[68:71]
	v_mfma_f32_16x16x32_bf16 v[64:67], v[170:173], v[216:219], v[64:67]
	v_mfma_f32_16x16x32_bf16 v[118:121], v[150:153], v[182:185], v[118:121]
	v_mfma_f32_16x16x32_bf16 v[114:117], v[174:177], v[182:185], v[114:117]
	v_mfma_f32_16x16x32_bf16 v[102:105], v[150:153], v[204:207], v[102:105]
	v_mfma_f32_16x16x32_bf16 v[98:101], v[174:177], v[204:207], v[98:101]
	v_mfma_f32_16x16x32_bf16 v[86:89], v[150:153], v[212:215], v[86:89]
	v_mfma_f32_16x16x32_bf16 v[82:85], v[174:177], v[212:215], v[82:85]
	v_mfma_f32_16x16x32_bf16 v[68:71], v[150:153], v[220:223], v[68:71]
	v_mfma_f32_16x16x32_bf16 v[64:67], v[174:177], v[220:223], v[64:67]
	s_barrier
	s_setprio 0
	s_add_i32 s57, s57, s26
	v_lshl_add_u64 v[186:187], s[20:21], 0, v[80:81]
	s_mov_b32 m0, s57
	ds_read_b128 v[178:181], v203 offset:16384
	ds_read_b128 v[182:185], v203 offset:17408
	ds_read_b128 v[196:199], v203 offset:18432
	ds_read_b128 v[204:207], v203 offset:19456
	ds_read_b128 v[208:211], v203 offset:20480
	ds_read_b128 v[212:215], v203 offset:21504
	ds_read_b128 v[216:219], v203 offset:22528
	ds_read_b128 v[220:223], v203 offset:23552
	global_load_lds_dwordx4 v[186:187], off
	s_add_i32 m0, s57, 0x2000
	s_add_u32 s58, s20, 0x40000
	v_lshl_add_u64 v[224:225], s[20:21], 0, v[160:161]
	s_addc_u32 s59, s21, 0
	s_add_i32 s57, s60, s26
	global_load_lds_dwordx4 v[224:225], off
	v_lshl_add_u64 v[226:227], s[58:59], 0, v[80:81]
	s_mov_b32 m0, s57
	v_lshl_add_u64 v[228:229], s[22:23], 0, v[162:163]
	global_load_lds_dwordx4 v[226:227], off
	v_lshl_add_u64 v[226:227], s[58:59], 0, v[160:161]
	s_add_i32 m0, s57, 0x2000
	s_nop 0
	global_load_lds_dwordx4 v[226:227], off
	v_lshl_add_u64 v[226:227], s[22:23], 0, v[164:165]
	s_mov_b32 m0, s27
	s_nop 0
	global_load_lds_dwordx4 v[226:227], off
	s_mov_b32 m0, s28
	s_nop 0
	global_load_lds_dwordx4 v[228:229], off
	s_waitcnt vmcnt(8)
	s_waitcnt lgkmcnt(0)
	s_setprio 1
	s_barrier
; #define PG8_STAGE(bufoff, gbase, voff) do { _Pragma("unroll") for (int _i = 0; _i < 2; ++_i) \
;         __builtin_amdgcn_global_load_lds((const unsigned*)((const char*)(gbase) + (voff)[_i]), (PG8_LAS unsigned*)(lds + (bufoff) + ldsw + _i * 8192), 16, 0, 0); } while (0)
; #define PG8_LDA(dst, b, h) do { _Pragma("unroll") for (int m = 0; m < 4; ++m) _Pragma("unroll") for (int k = 0; k < 2; ++k) dst[m][k] = *(const PG8_LAS bf16x8*)(lds + PG8_SA(b, h) + aoff + m * 2048 + k * 1024); } while (0)
; #define PG8_LDB(dst, b, h) do { _Pragma("unroll") for (int n = 0; n < 2; ++n) _Pragma("unroll") for (int k = 0; k < 2; ++k) dst[n][k] = *(const PG8_LAS bf16x8*)(lds + PG8_SB(b, h) + boff + n * 2048 + k * 1024); } while (0)
; #define PG8_MMA(ai, bj, At, Bt) do { __builtin_amdgcn_s_setprio(1); _Pragma("unroll") for (int m = 0; m < 4; ++m) _Pragma("unroll") for (int n = 0; n < 2; ++n) _Pragma("unroll") for (int k = 0; k < 2; ++k) \
;         acc[ai][bj][m][n] = __builtin_amdgcn_mfma_f32_16x16x32_bf16(Bt[n][k], At[m][k], acc[ai][bj][m][n], 0, 0, 0); __builtin_amdgcn_s_setprio(0); } while (0)
; #define PG8_WAIT_V(n) asm volatile("s_waitcnt vmcnt(" #n ")" ::: "memory")
; #define PG8_WAIT_L(n) asm volatile("s_waitcnt lgkmcnt(" #n ")" ::: "memory")
; #define PG8_BAR __builtin_amdgcn_s_barrier()
; #define PG8_SCHED __builtin_amdgcn_sched_barrier(0)
; template <class Epi, class Sched, bool ALIGN_EPI = false, bool SP2 = false, bool HALFM = false>
; __device__ __forceinline__ void gemm_phase(PG8_LAS unsigned char* lds, const Gemm g, const Sched& S, const Epi& E) {
;     ...
;             PG8_WAIT_V(8); PG8_WAIT_L(0); PG8_BAR; if constexpr (!HALFM) { PG8_MMA(1, 0, At, B0); PG8_MMA(1, 1, At, B1); } PG8_BAR; PG8_SCHED;
;             PG8_LDB(B0, 1, 0); PG8_LDB(B1, 1, 1); PG8_SCHED; PG8_LDA(At, 1, 0); PG8_STAGE(PG8_SA(0, 1), a2 + hstep, voffA);
;             PG8_WAIT_V(8); PG8_WAIT_L(0); PG8_BAR; PG8_MMA(0, 0, At, B0); PG8_MMA(0, 1, At, B1); PG8_BAR; PG8_SCHED;
	v_mfma_f32_16x16x32_bf16 v[60:63], v[130:133], v[178:181], v[60:63]
	v_mfma_f32_16x16x32_bf16 v[56:59], v[138:141], v[178:181], v[56:59]
	v_mfma_f32_16x16x32_bf16 v[44:47], v[130:133], v[196:199], v[44:47]
	v_mfma_f32_16x16x32_bf16 v[40:43], v[138:141], v[196:199], v[40:43]
	v_mfma_f32_16x16x32_bf16 v[28:31], v[130:133], v[208:211], v[28:31]
	v_mfma_f32_16x16x32_bf16 v[24:27], v[138:141], v[208:211], v[24:27]
	v_mfma_f32_16x16x32_bf16 v[12:15], v[130:133], v[216:219], v[12:15]
	v_mfma_f32_16x16x32_bf16 v[8:11], v[138:141], v[216:219], v[8:11]
	v_mfma_f32_16x16x32_bf16 v[60:63], v[134:137], v[182:185], v[60:63]
	v_mfma_f32_16x16x32_bf16 v[56:59], v[142:145], v[182:185], v[56:59]
	v_mfma_f32_16x16x32_bf16 v[44:47], v[134:137], v[204:207], v[44:47]
	v_mfma_f32_16x16x32_bf16 v[40:43], v[142:145], v[204:207], v[40:43]
	v_mfma_f32_16x16x32_bf16 v[28:31], v[134:137], v[212:215], v[28:31]
	v_mfma_f32_16x16x32_bf16 v[24:27], v[142:145], v[212:215], v[24:27]
	v_mfma_f32_16x16x32_bf16 v[12:15], v[134:137], v[220:223], v[12:15]
	v_mfma_f32_16x16x32_bf16 v[8:11], v[142:145], v[220:223], v[8:11]
	v_mfma_f32_16x16x32_bf16 v[52:55], v[146:149], v[178:181], v[52:55]
	v_mfma_f32_16x16x32_bf16 v[48:51], v[170:173], v[178:181], v[48:51]
	v_mfma_f32_16x16x32_bf16 v[36:39], v[146:149], v[196:199], v[36:39]
	v_mfma_f32_16x16x32_bf16 v[32:35], v[170:173], v[196:199], v[32:35]
	v_mfma_f32_16x16x32_bf16 v[20:23], v[146:149], v[208:211], v[20:23]
	v_mfma_f32_16x16x32_bf16 v[16:19], v[170:173], v[208:211], v[16:19]
	v_mfma_f32_16x16x32_bf16 v[4:7], v[146:149], v[216:219], v[4:7]
	v_mfma_f32_16x16x32_bf16 v[0:3], v[170:173], v[216:219], v[0:3]
	v_mfma_f32_16x16x32_bf16 v[52:55], v[150:153], v[182:185], v[52:55]
	v_mfma_f32_16x16x32_bf16 v[48:51], v[174:177], v[182:185], v[48:51]
	v_mfma_f32_16x16x32_bf16 v[36:39], v[150:153], v[204:207], v[36:39]
	v_mfma_f32_16x16x32_bf16 v[32:35], v[174:177], v[204:207], v[32:35]
	v_mfma_f32_16x16x32_bf16 v[20:23], v[150:153], v[212:215], v[20:23]
	v_mfma_f32_16x16x32_bf16 v[16:19], v[174:177], v[212:215], v[16:19]
	v_mfma_f32_16x16x32_bf16 v[4:7], v[150:153], v[220:223], v[4:7]
	v_mfma_f32_16x16x32_bf16 v[0:3], v[174:177], v[220:223], v[0:3]
	s_barrier
	s_setprio 0
	s_add_i32 s57, 0, 0x18000
	s_add_i32 s58, 0, 0x1c000
	v_add_u32_e32 v142, s57, v189
	v_add_u32_e32 v174, s58, v189
	ds_read_b128 v[130:133], v142
	ds_read_b128 v[134:137], v142 offset:1024
	ds_read_b128 v[138:141], v142 offset:2048
	ds_read_b128 v[142:145], v142 offset:3072
	ds_read_b128 v[146:149], v174
	ds_read_b128 v[150:153], v174 offset:1024
	ds_read_b128 v[170:173], v174 offset:2048
	ds_read_b128 v[174:177], v174 offset:3072
	s_add_u32 s22, s22, 0x40000
	s_addc_u32 s23, s23, 0
	s_mov_b32 m0, s29
	v_lshl_add_u64 v[230:231], s[22:23], 0, v[164:165]
	ds_read_b128 v[178:181], v203 offset:32768
	ds_read_b128 v[182:185], v203 offset:33792
	ds_read_b128 v[196:199], v203 offset:34816
	ds_read_b128 v[204:207], v203 offset:35840
	ds_read_b128 v[208:211], v203 offset:36864
	ds_read_b128 v[212:215], v203 offset:37888
	ds_read_b128 v[216:219], v203 offset:38912
	ds_read_b128 v[220:223], v203 offset:39936
	global_load_lds_dwordx4 v[230:231], off
	v_lshl_add_u64 v[230:231], s[22:23], 0, v[162:163]
	s_mov_b32 m0, s45
	s_nop 0
	global_load_lds_dwordx4 v[230:231], off
	s_waitcnt vmcnt(8)
	s_waitcnt lgkmcnt(0)
	s_setprio 1
	s_barrier
	v_mfma_f32_16x16x32_bf16 v[126:129], v[130:133], v[178:181], v[126:129]
	v_mfma_f32_16x16x32_bf16 v[122:125], v[138:141], v[178:181], v[122:125]
	v_mfma_f32_16x16x32_bf16 v[110:113], v[130:133], v[196:199], v[110:113]
	v_mfma_f32_16x16x32_bf16 v[106:109], v[138:141], v[196:199], v[106:109]
	v_mfma_f32_16x16x32_bf16 v[94:97], v[130:133], v[208:211], v[94:97]
	v_mfma_f32_16x16x32_bf16 v[90:93], v[138:141], v[208:211], v[90:93]
	v_mfma_f32_16x16x32_bf16 v[76:79], v[130:133], v[216:219], v[76:79]
	v_mfma_f32_16x16x32_bf16 v[72:75], v[138:141], v[216:219], v[72:75]
	v_mfma_f32_16x16x32_bf16 v[126:129], v[134:137], v[182:185], v[126:129]
	v_mfma_f32_16x16x32_bf16 v[122:125], v[142:145], v[182:185], v[122:125]
	v_mfma_f32_16x16x32_bf16 v[110:113], v[134:137], v[204:207], v[110:113]
	v_mfma_f32_16x16x32_bf16 v[106:109], v[142:145], v[204:207], v[106:109]
	v_mfma_f32_16x16x32_bf16 v[94:97], v[134:137], v[212:215], v[94:97]
	v_mfma_f32_16x16x32_bf16 v[90:93], v[142:145], v[212:215], v[90:93]
	v_mfma_f32_16x16x32_bf16 v[76:79], v[134:137], v[220:223], v[76:79]
	v_mfma_f32_16x16x32_bf16 v[72:75], v[142:145], v[220:223], v[72:75]
	v_mfma_f32_16x16x32_bf16 v[118:121], v[146:149], v[178:181], v[118:121]
	v_mfma_f32_16x16x32_bf16 v[114:117], v[170:173], v[178:181], v[114:117]
	v_mfma_f32_16x16x32_bf16 v[102:105], v[146:149], v[196:199], v[102:105]
	v_mfma_f32_16x16x32_bf16 v[98:101], v[170:173], v[196:199], v[98:101]
	v_mfma_f32_16x16x32_bf16 v[86:89], v[146:149], v[208:211], v[86:89]
	v_mfma_f32_16x16x32_bf16 v[82:85], v[170:173], v[208:211], v[82:85]
	v_mfma_f32_16x16x32_bf16 v[68:71], v[146:149], v[216:219], v[68:71]
	v_mfma_f32_16x16x32_bf16 v[64:67], v[170:173], v[216:219], v[64:67]
	v_mfma_f32_16x16x32_bf16 v[118:121], v[150:153], v[182:185], v[118:121]
	v_mfma_f32_16x16x32_bf16 v[114:117], v[174:177], v[182:185], v[114:117]
	v_mfma_f32_16x16x32_bf16 v[102:105], v[150:153], v[204:207], v[102:105]
	v_mfma_f32_16x16x32_bf16 v[98:101], v[174:177], v[204:207], v[98:101]
	v_mfma_f32_16x16x32_bf16 v[86:89], v[150:153], v[212:215], v[86:89]
	v_mfma_f32_16x16x32_bf16 v[82:85], v[174:177], v[212:215], v[82:85]
	v_mfma_f32_16x16x32_bf16 v[68:71], v[150:153], v[220:223], v[68:71]
	v_mfma_f32_16x16x32_bf16 v[64:67], v[174:177], v[220:223], v[64:67]
	s_barrier
; #define PG8_STAGE(bufoff, gbase, voff) do { _Pragma("unroll") for (int _i = 0; _i < 2; ++_i) \
;         __builtin_amdgcn_global_load_lds((const unsigned*)((const char*)(gbase) + (voff)[_i]), (PG8_LAS unsigned*)(lds + (bufoff) + ldsw + _i * 8192), 16, 0, 0); } while (0)
; #define PG8_LDA(dst, b, h) do { _Pragma("unroll") for (int m = 0; m < 4; ++m) _Pragma("unroll") for (int k = 0; k < 2; ++k) dst[m][k] = *(const PG8_LAS bf16x8*)(lds + PG8_SA(b, h) + aoff + m * 2048 + k * 1024); } while (0)
; #define PG8_MMA(ai, bj, At, Bt) do { __builtin_amdgcn_s_setprio(1); _Pragma("unroll") for (int m = 0; m < 4; ++m) _Pragma("unroll") for (int n = 0; n < 2; ++n) _Pragma("unroll") for (int k = 0; k < 2; ++k) \
;         acc[ai][bj][m][n] = __builtin_amdgcn_mfma_f32_16x16x32_bf16(Bt[n][k], At[m][k], acc[ai][bj][m][n], 0, 0, 0); __builtin_amdgcn_s_setprio(0); } while (0)
; #define PG8_WAIT_V(n) asm volatile("s_waitcnt vmcnt(" #n ")" ::: "memory")
; #define PG8_WAIT_L(n) asm volatile("s_waitcnt lgkmcnt(" #n ")" ::: "memory")
; #define PG8_BAR __builtin_amdgcn_s_barrier()
; #define PG8_SCHED __builtin_amdgcn_sched_barrier(0)
; template <class Epi, class Sched, bool ALIGN_EPI = false, bool SP2 = false, bool HALFM = false>
; __device__ __forceinline__ void gemm_phase(PG8_LAS unsigned char* lds, const Gemm g, const Sched& S, const Epi& E) {
;     ...
;         for (int t = 0; t < nt; t += 2) {
;     ...
;             if constexpr (!HALFM) PG8_LDA(At, 1, 1); PG8_STAGE(PG8_SB(1, 0), b3, voffB); PG8_STAGE(PG8_SB(1, 1), b3 + hstep, voffB); PG8_STAGE(PG8_SA(1, 0), a3, voffA);
;             PG8_WAIT_V(8); PG8_WAIT_L(0); PG8_BAR; if constexpr (!HALFM) { PG8_MMA(1, 0, At, B0); PG8_MMA(1, 1, At, B1); } PG8_BAR; PG8_SCHED;
	s_setprio 0
	s_add_i32 s22, s57, s26
	v_lshl_add_u64 v[186:187], v[186:187], 0, s[82:83]
	s_mov_b32 m0, s22
	ds_read_b128 v[178:181], v203 offset:49152
	ds_read_b128 v[182:185], v203 offset:50176
	ds_read_b128 v[196:199], v203 offset:51200
	ds_read_b128 v[204:207], v203 offset:52224
	ds_read_b128 v[208:211], v203 offset:53248
	ds_read_b128 v[212:215], v203 offset:54272
	ds_read_b128 v[216:219], v203 offset:55296
	ds_read_b128 v[220:223], v203 offset:56320
	global_load_lds_dwordx4 v[186:187], off
	s_add_i32 m0, s22, 0x2000
	s_add_u32 s20, s20, 0x40080
	v_lshl_add_u64 v[186:187], v[224:225], 0, s[82:83]
	s_addc_u32 s21, s21, 0
	s_add_i32 s22, s58, s26
	global_load_lds_dwordx4 v[186:187], off
	v_lshl_add_u64 v[186:187], s[20:21], 0, v[80:81]
	s_mov_b32 m0, s22
	s_nop 0
	global_load_lds_dwordx4 v[186:187], off
	v_lshl_add_u64 v[186:187], s[20:21], 0, v[160:161]
	s_add_i32 m0, s22, 0x2000
	s_nop 0
	global_load_lds_dwordx4 v[186:187], off
	v_lshl_add_u64 v[186:187], v[226:227], 0, s[82:83]
	s_mov_b32 m0, s47
	s_nop 0
	global_load_lds_dwordx4 v[186:187], off
	v_lshl_add_u64 v[186:187], v[228:229], 0, s[82:83]
	s_mov_b32 m0, s48
	s_nop 0
	global_load_lds_dwordx4 v[186:187], off
	s_waitcnt vmcnt(8)
	s_waitcnt lgkmcnt(0)
	s_setprio 1
	s_barrier
	v_mfma_f32_16x16x32_bf16 v[60:63], v[130:133], v[178:181], v[60:63]
	v_mfma_f32_16x16x32_bf16 v[56:59], v[138:141], v[178:181], v[56:59]
	v_mfma_f32_16x16x32_bf16 v[44:47], v[130:133], v[196:199], v[44:47]
	v_mfma_f32_16x16x32_bf16 v[40:43], v[138:141], v[196:199], v[40:43]
	v_mfma_f32_16x16x32_bf16 v[28:31], v[130:133], v[208:211], v[28:31]
	v_mfma_f32_16x16x32_bf16 v[24:27], v[138:141], v[208:211], v[24:27]
	v_mfma_f32_16x16x32_bf16 v[12:15], v[130:133], v[216:219], v[12:15]
	v_mfma_f32_16x16x32_bf16 v[8:11], v[138:141], v[216:219], v[8:11]
	v_mfma_f32_16x16x32_bf16 v[60:63], v[134:137], v[182:185], v[60:63]
	v_mfma_f32_16x16x32_bf16 v[56:59], v[142:145], v[182:185], v[56:59]
	v_mfma_f32_16x16x32_bf16 v[44:47], v[134:137], v[204:207], v[44:47]
	v_mfma_f32_16x16x32_bf16 v[40:43], v[142:145], v[204:207], v[40:43]
	v_mfma_f32_16x16x32_bf16 v[28:31], v[134:137], v[212:215], v[28:31]
	v_mfma_f32_16x16x32_bf16 v[24:27], v[142:145], v[212:215], v[24:27]
	v_mfma_f32_16x16x32_bf16 v[12:15], v[134:137], v[220:223], v[12:15]
	v_mfma_f32_16x16x32_bf16 v[8:11], v[142:145], v[220:223], v[8:11]
	v_mfma_f32_16x16x32_bf16 v[52:55], v[146:149], v[178:181], v[52:55]
	v_mfma_f32_16x16x32_bf16 v[48:51], v[170:173], v[178:181], v[48:51]
	v_mfma_f32_16x16x32_bf16 v[36:39], v[146:149], v[196:199], v[36:39]
	v_mfma_f32_16x16x32_bf16 v[32:35], v[170:173], v[196:199], v[32:35]
	v_mfma_f32_16x16x32_bf16 v[20:23], v[146:149], v[208:211], v[20:23]
	v_mfma_f32_16x16x32_bf16 v[16:19], v[170:173], v[208:211], v[16:19]
	v_mfma_f32_16x16x32_bf16 v[4:7], v[146:149], v[216:219], v[4:7]
	v_mfma_f32_16x16x32_bf16 v[0:3], v[170:173], v[216:219], v[0:3]
	v_mfma_f32_16x16x32_bf16 v[52:55], v[150:153], v[182:185], v[52:55]
	v_mfma_f32_16x16x32_bf16 v[48:51], v[174:177], v[182:185], v[48:51]
	v_mfma_f32_16x16x32_bf16 v[36:39], v[150:153], v[204:207], v[36:39]
	v_mfma_f32_16x16x32_bf16 v[32:35], v[174:177], v[204:207], v[32:35]
	v_mfma_f32_16x16x32_bf16 v[20:23], v[150:153], v[212:215], v[20:23]
	v_mfma_f32_16x16x32_bf16 v[16:19], v[174:177], v[212:215], v[16:19]
	v_mfma_f32_16x16x32_bf16 v[4:7], v[150:153], v[220:223], v[4:7]
	v_mfma_f32_16x16x32_bf16 v[0:3], v[174:177], v[220:223], v[0:3]
	s_barrier
	s_setprio 0
	s_add_i32 s56, s56, 2
	s_add_u32 s18, s18, 0x100
	s_addc_u32 s19, s19, 0
	s_add_u32 s54, s54, 0x100
	s_addc_u32 s55, s55, 0
	s_cmp_gt_u32 s56, 13
	s_cbranch_scc0 .LBB0_1165
	s_and_b64 vcc, exec, s[8:9]
	s_cbranch_vccz .LBB0_1168
	s_barrier
